# K-loop heads at byte phase 40 mod 64 instead of 8
# speedup vs baseline: 1.0158x; 1.0002x over previous
;     __device__ __forceinline__ size_t a_off(const Unit& u) const { return (size_t)u.pm * atile; }
;     __device__ __forceinline__ size_t b_off(const Unit& u) const { return (size_t)u.pn * btile; }
;     __device__ __forceinline__ bool next(int i, Unit& u) const { const long L = (long)i * G + c; if (L >= NG * 8) return false; u.g = (int)(L >> 3); u.pm = (int)(L & 7); u.pn = 0; return true; }
;     __device__ __forceinline__ size_t a_off(const Unit& u) const { return ((size_t)u.g * NROW + (size_t)u.pm * BM) * KA * 2; }
; #define PG8_WAIT_V(n) asm volatile("s_waitcnt vmcnt(" #n ")" ::: "memory")
;     ...
;         const bool has_next = S.next(ui + 1, nxt);
;         const char* nA = has_next ? (const char*)Ap + S.a_off(nxt) : cA; const char* nB = has_next ? (const char*)Btp + S.b_off(nxt) : cB;
;         for (int t = 0; t < nt; t += 2) {
;             const bool last = (t == nt - 2);
;             const char* a1 = cA + (size_t)(t + 1) * kstep;
;             const char* a2 = last ? nA : cA + (size_t)(t + 2) * kstep; const char* b2 = last ? nB : cB + (size_t)(t + 2) * kstep;
;             const char* a3 = a2 + kstep; const char* b3 = b2 + kstep;
;             PG8_LDB(B0, 0, 0); PG8_SCHED; PG8_LDA(At, 0, 0); PG8_STAGE(PG8_SA(1, 1), a1 + hstepA, voffA);
;             PG8_WAIT_L(8); PG8_BAR; PG8_WAIT_L(0); PG8_MMA(0, 0, At, B0); PG8_BAR; PG8_SCHED;
;             PG8_LDB(B1, 0, 1); PG8_STAGE(PG8_SB(0, 0), b2, voffB);
;             PG8_BAR; PG8_WAIT_L(0); PG8_MMA(0, 1, At, B1); PG8_BAR;
;             PG8_LDA(At, 0, 1); PG8_STAGE(PG8_SA(0, 0), a2, voffA);
;             PG8_BAR; PG8_WAIT_L(0); PG8_MMA(1, 0, At, B0); PG8_BAR; PG8_SCHED;
;             PG8_STAGE(PG8_SB(0, 1), b2 + hstepB, voffB);
;             PG8_WAIT_V(6); PG8_BAR; PG8_MMA(1, 1, At, B1); PG8_BAR;
;             PG8_LDB(B0, 1, 0); PG8_SCHED; PG8_LDA(At, 1, 0); PG8_STAGE(PG8_SA(0, 1), a2 + hstepA, voffA);
;             PG8_WAIT_L(8); PG8_BAR; PG8_WAIT_L(0); PG8_MMA(0, 0, At, B0); PG8_BAR; PG8_SCHED;
;             PG8_LDB(B1, 1, 1); PG8_STAGE(PG8_SB(1, 0), b3, voffB);
;             PG8_BAR; PG8_WAIT_L(0); PG8_MMA(0, 1, At, B1); PG8_BAR;
;             PG8_LDA(At, 1, 1); PG8_STAGE(PG8_SA(1, 0), a3, voffA);
;             PG8_BAR; PG8_WAIT_L(0); PG8_MMA(1, 0, At, B0); PG8_BAR; PG8_SCHED;
;             PG8_STAGE(PG8_SB(1, 1), b3 + hstepB, voffB);
;             PG8_WAIT_V(6); PG8_BAR; PG8_MMA(1, 1, At, B1); PG8_BAR;
.LBB0_505:
	s_andn2_b64 vcc, exec, s[52:53]
	s_cbranch_vccnz .Lkzero_507
	s_add_u32 s17, s36, 0x100
	s_addc_u32 s22, s37, 0
	s_add_u32 s8, s36, s6
	s_addc_u32 s9, s37, s7
	s_add_u32 s23, s8, 0x80
	s_addc_u32 s24, s9, 0
	s_mov_b32 s26, 0
	s_mov_b64 s[8:9], 0
	s_add_i32 s25, s26, 2
	s_add_u32 s72, s8, 0x100
	s_addc_u32 s73, s9, 0
	s_add_u32 s27, s17, s8
	ds_read_b128 v[76:79], v73
	ds_read_b128 v[80:83], v73 offset:1024
	ds_read_b128 v[84:87], v73 offset:2048
	ds_read_b128 v[88:91], v73 offset:3072
	s_addc_u32 s28, s22, s9
	s_cmp_eq_u32 s93, s26
	s_cselect_b32 s64, s58, s27
	s_cselect_b32 s26, s59, s28
	s_cselect_b32 s27, 0, s73
	s_cselect_b32 s28, 0, s72
	s_add_u32 s36, s64, 0x80
	s_addc_u32 s29, s26, 0
	s_add_u32 s44, s4, s28
	s_addc_u32 s27, s82, s27
	s_add_u32 s8, s23, s8
	s_addc_u32 s9, s24, s9
	s_and_b32 s9, s9, 0xffff
	s_mov_b32 m0, s31
	ds_read_b128 v[92:95], v74
	ds_read_b128 v[96:99], v74 offset:1024
	ds_read_b128 v[100:103], v74 offset:2048
	ds_read_b128 v[104:107], v74 offset:3072
	ds_read_b128 v[108:111], v74 offset:4096
	ds_read_b128 v[112:115], v74 offset:5120
	ds_read_b128 v[116:119], v74 offset:6144
	ds_read_b128 v[120:123], v74 offset:7168
	buffer_load_dwordx4 v67, s[8:11], 0 offen lds
	s_mov_b32 m0, s74
	s_nop 0
	buffer_load_dwordx4 v71, s[8:11], 0 offen lds
	s_waitcnt lgkmcnt(8)
	s_barrier
	s_waitcnt lgkmcnt(0)
	s_setprio 1
	s_waitcnt lgkmcnt(7)
	v_mfma_f32_16x16x32_bf16 v[60:63], v[76:79], v[92:95], 0
	v_mfma_f32_16x16x32_bf16 v[56:59], v[84:87], v[92:95], 0
	s_waitcnt lgkmcnt(5)
	v_mfma_f32_16x16x32_bf16 v[52:55], v[76:79], v[100:103], 0
	v_mfma_f32_16x16x32_bf16 v[48:51], v[84:87], v[100:103], 0
	s_waitcnt lgkmcnt(3)
	v_mfma_f32_16x16x32_bf16 v[44:47], v[76:79], v[108:111], 0
	v_mfma_f32_16x16x32_bf16 v[40:43], v[84:87], v[108:111], 0
	s_waitcnt lgkmcnt(1)
	v_mfma_f32_16x16x32_bf16 v[36:39], v[76:79], v[116:119], 0
	v_mfma_f32_16x16x32_bf16 v[32:35], v[84:87], v[116:119], 0
	v_mfma_f32_16x16x32_bf16 v[60:63], v[80:83], v[96:99], v[60:63]
	v_mfma_f32_16x16x32_bf16 v[56:59], v[88:91], v[96:99], v[56:59]
	v_mfma_f32_16x16x32_bf16 v[52:55], v[80:83], v[104:107], v[52:55]
	v_mfma_f32_16x16x32_bf16 v[48:51], v[88:91], v[104:107], v[48:51]
	v_mfma_f32_16x16x32_bf16 v[44:47], v[80:83], v[112:115], v[44:47]
	v_mfma_f32_16x16x32_bf16 v[40:43], v[88:91], v[112:115], v[40:43]
	s_waitcnt lgkmcnt(0)
	v_mfma_f32_16x16x32_bf16 v[36:39], v[80:83], v[120:123], v[36:39]
	v_mfma_f32_16x16x32_bf16 v[32:35], v[88:91], v[120:123], v[32:35]
	s_setprio 0
	s_barrier
	s_and_b32 s45, s27, 0xffff
	s_mov_b32 s46, s10
	s_mov_b32 s47, s11
	s_mov_b32 m0, s84
	s_nop 0
	buffer_load_dwordx4 v70, s[44:47], 0 offen lds
	s_mov_b32 m0, s86
	s_nop 0
	buffer_load_dwordx4 v72, s[44:47], 0 offen lds
	s_barrier
	s_waitcnt lgkmcnt(0)
	s_setprio 1
	s_setprio 0
	s_and_b32 s65, s26, 0xffff
	s_mov_b32 s66, s10
	s_mov_b32 s67, s11
	s_mov_b32 m0, s75
	s_barrier
	ds_read_b128 v[92:95], v74 offset:16384
	ds_read_b128 v[96:99], v74 offset:17408
	ds_read_b128 v[100:103], v74 offset:18432
	ds_read_b128 v[104:107], v74 offset:19456
	ds_read_b128 v[108:111], v74 offset:20480
	ds_read_b128 v[112:115], v74 offset:21504
	ds_read_b128 v[116:119], v74 offset:22528
	ds_read_b128 v[120:123], v74 offset:23552
	buffer_load_dwordx4 v67, s[64:67], 0 offen lds
	s_mov_b32 m0, s5
	s_nop 0
	buffer_load_dwordx4 v71, s[64:67], 0 offen lds
	s_barrier
	s_waitcnt lgkmcnt(0)
	s_setprio 1
	s_waitcnt lgkmcnt(7)
	v_mfma_f32_16x16x32_bf16 v[28:31], v[76:79], v[92:95], 0
	v_mfma_f32_16x16x32_bf16 v[24:27], v[84:87], v[92:95], 0
	s_waitcnt lgkmcnt(5)
	v_mfma_f32_16x16x32_bf16 v[20:23], v[76:79], v[100:103], 0
	v_mfma_f32_16x16x32_bf16 v[16:19], v[84:87], v[100:103], 0
	s_waitcnt lgkmcnt(3)
	v_mfma_f32_16x16x32_bf16 v[12:15], v[76:79], v[108:111], 0
	v_mfma_f32_16x16x32_bf16 v[8:11], v[84:87], v[108:111], 0
	s_waitcnt lgkmcnt(1)
	v_mfma_f32_16x16x32_bf16 v[4:7], v[76:79], v[116:119], 0
	v_mfma_f32_16x16x32_bf16 v[0:3], v[84:87], v[116:119], 0
	v_mfma_f32_16x16x32_bf16 v[28:31], v[80:83], v[96:99], v[28:31]
	v_mfma_f32_16x16x32_bf16 v[24:27], v[88:91], v[96:99], v[24:27]
	v_mfma_f32_16x16x32_bf16 v[20:23], v[80:83], v[104:107], v[20:23]
	v_mfma_f32_16x16x32_bf16 v[16:19], v[88:91], v[104:107], v[16:19]
	v_mfma_f32_16x16x32_bf16 v[12:15], v[80:83], v[112:115], v[12:15]
	v_mfma_f32_16x16x32_bf16 v[8:11], v[88:91], v[112:115], v[8:11]
	s_waitcnt lgkmcnt(0)
	v_mfma_f32_16x16x32_bf16 v[4:7], v[80:83], v[120:123], v[4:7]
	v_mfma_f32_16x16x32_bf16 v[0:3], v[88:91], v[120:123], v[0:3]
	s_setprio 0
	s_barrier
	s_add_u32 s8, s44, s50
	s_addc_u32 s28, s27, s51
	s_and_b32 s9, s28, 0xffff
	s_mov_b32 m0, s87
	s_nop 0
	buffer_load_dwordx4 v70, s[8:11], 0 offen lds
	s_mov_b32 m0, s89
	s_nop 0
	buffer_load_dwordx4 v72, s[8:11], 0 offen lds
	s_waitcnt vmcnt(6)
	s_barrier
	s_setprio 1
	s_setprio 0
	s_barrier
	s_branch .Lkmid_507
	.p2align 6
	s_nop 0
	s_nop 0
	s_nop 0
	s_nop 0
	s_nop 0
	s_nop 0
	s_nop 0
	s_nop 0
	s_nop 0
	s_nop 0

; #define PG8_STAGE(bufoff, gbase, voff) do { const __amdgpu_buffer_rsrc_t _r = __builtin_amdgcn_make_buffer_rsrc((void*)(gbase), (short)0, 0x7fffffff, 0x00020000); _Pragma("unroll") for (int _i = 0; _i < 2; ++_i) \
;         __builtin_amdgcn_raw_ptr_buffer_load_lds(_r, (LAS unsigned*)(lds + (bufoff) + ldsw + _i * 8192), 16, (int)(voff)[_i], 0, 0, 0); } while (0)
; #define PG8_LDA(dst, b, h) do { _Pragma("unroll") for (int m = 0; m < 4; ++m) _Pragma("unroll") for (int k = 0; k < 2; ++k) dst[m][k] = *(const LAS bf16x8*)(lds + PG8_SA(b, h) + aoff + m * 2048 + k * 1024); } while (0)
; #define PG8_LDB(dst, b, h) do { _Pragma("unroll") for (int n = 0; n < 2; ++n) _Pragma("unroll") for (int k = 0; k < 2; ++k) dst[n][k] = *(const LAS bf16x8*)(lds + PG8_SB(b, h) + boff + n * 2048 + k * 1024); } while (0)
; #define PG8_MMA(ai, bj, At, Bt) do { __builtin_amdgcn_s_setprio(1); _Pragma("unroll") for (int k = 0; k < 2; ++k) _Pragma("unroll") for (int m = 0; m < 4; ++m) _Pragma("unroll") for (int n = 0; n < ((bj) == 1 ? NB1 : 2); ++n) \
;         acc[ai][bj][m][n] = __builtin_amdgcn_mfma_f32_16x16x32_bf16(Bt[n][k], At[m][k], acc[ai][bj][m][n], 0, 0, 0); __builtin_amdgcn_s_setprio(0); } while (0)
; #define PG8_WAIT_V(n) asm volatile("s_waitcnt vmcnt(" #n ")" ::: "memory")
; #define PG8_WAIT_L(n) asm volatile("s_waitcnt lgkmcnt(" #n ")" ::: "memory")
; #define PG8_BAR __builtin_amdgcn_s_barrier()
;     ...
;         for (int t = 0; t < nt; t += 2) {
;             const bool last = (t == nt - 2);
;             const char* a1 = cA + (size_t)(t + 1) * kstep;
;             const char* a2 = last ? nA : cA + (size_t)(t + 2) * kstep; const char* b2 = last ? nB : cB + (size_t)(t + 2) * kstep;
;             const char* a3 = a2 + kstep; const char* b3 = b2 + kstep;
;             PG8_LDB(B0, 0, 0); PG8_SCHED; PG8_LDA(At, 0, 0); PG8_STAGE(PG8_SA(1, 1), a1 + hstepA, voffA);
;             PG8_WAIT_L(8); PG8_BAR; PG8_WAIT_L(0); PG8_MMA(0, 0, At, B0); PG8_BAR; PG8_SCHED;
;             PG8_LDB(B1, 0, 1); PG8_STAGE(PG8_SB(0, 0), b2, voffB);
;             PG8_BAR; PG8_WAIT_L(0); PG8_MMA(0, 1, At, B1); PG8_BAR;
;             PG8_LDA(At, 0, 1); PG8_STAGE(PG8_SA(0, 0), a2, voffA);
;             PG8_BAR; PG8_WAIT_L(0); PG8_MMA(1, 0, At, B0); PG8_BAR; PG8_SCHED;
;             PG8_STAGE(PG8_SB(0, 1), b2 + hstepB, voffB);
;             PG8_WAIT_V(6); PG8_BAR; PG8_MMA(1, 1, At, B1); PG8_BAR;
.LBB0_573:
	s_andn2_b64 vcc, exec, s[20:21]
	s_cbranch_vccnz .Lkzero_575
	s_add_u32 s45, s26, 0x100
	s_addc_u32 s47, s27, 0
	s_add_u32 s51, s24, 0x100
	s_addc_u32 s81, s25, 0
	s_mov_b32 s8, 0
	ds_read_b128 v[96:99], v215
	ds_read_b128 v[100:103], v215 offset:1024
	ds_read_b128 v[136:139], v215 offset:2048
	ds_read_b128 v[140:143], v215 offset:3072
	s_add_i32 s16, s8, 2
	s_cmp_eq_u32 s90, s8
	s_cselect_b32 s36, s42, s45
	s_cselect_b32 s23, s43, s47
	s_cselect_b32 s22, s1, s81
	s_cselect_b32 s28, s0, s51
	s_add_u32 s24, s36, 0x80
	s_addc_u32 s17, s23, 0
	s_add_u32 s8, s45, s6
	s_addc_u32 s9, s47, s7
	s_add_u32 s8, s8, 0xffffff80
	s_addc_u32 s9, s9, -1
	s_and_b32 s9, s9, 0xffff
	s_mov_b32 m0, s76
	ds_read_b128 v[144:147], v216
	ds_read_b128 v[148:151], v216 offset:1024
	ds_read_b128 v[152:155], v216 offset:2048
	ds_read_b128 v[156:159], v216 offset:3072
	ds_read_b128 v[160:163], v216 offset:4096
	ds_read_b128 v[164:167], v216 offset:5120
	ds_read_b128 v[168:171], v216 offset:6144
	ds_read_b128 v[172:175], v216 offset:7168
	buffer_load_dwordx4 v210, s[8:11], 0 offen lds
	s_mov_b32 m0, s77
	s_nop 0
	buffer_load_dwordx4 v212, s[8:11], 0 offen lds
	s_waitcnt lgkmcnt(8)
	s_barrier
	s_waitcnt lgkmcnt(0)
	s_setprio 1
	s_waitcnt lgkmcnt(7)
	v_mfma_f32_16x16x32_bf16 v[132:135], v[96:99], v[144:147], 0
	v_mfma_f32_16x16x32_bf16 v[120:123], v[136:139], v[144:147], 0
	s_waitcnt lgkmcnt(5)
	v_mfma_f32_16x16x32_bf16 v[116:119], v[96:99], v[152:155], 0
	v_mfma_f32_16x16x32_bf16 v[112:115], v[136:139], v[152:155], 0
	s_waitcnt lgkmcnt(3)
	v_mfma_f32_16x16x32_bf16 v[92:95], v[96:99], v[160:163], 0
	v_mfma_f32_16x16x32_bf16 v[88:91], v[136:139], v[160:163], 0
	s_waitcnt lgkmcnt(1)
	v_mfma_f32_16x16x32_bf16 v[76:79], v[96:99], v[168:171], 0
	v_mfma_f32_16x16x32_bf16 v[72:75], v[136:139], v[168:171], 0
	v_mfma_f32_16x16x32_bf16 v[132:135], v[100:103], v[148:151], v[132:135]
	v_mfma_f32_16x16x32_bf16 v[120:123], v[140:143], v[148:151], v[120:123]
	v_mfma_f32_16x16x32_bf16 v[116:119], v[100:103], v[156:159], v[116:119]
	v_mfma_f32_16x16x32_bf16 v[112:115], v[140:143], v[156:159], v[112:115]
	v_mfma_f32_16x16x32_bf16 v[92:95], v[100:103], v[164:167], v[92:95]
	v_mfma_f32_16x16x32_bf16 v[88:91], v[140:143], v[164:167], v[88:91]
	s_waitcnt lgkmcnt(0)
	v_mfma_f32_16x16x32_bf16 v[76:79], v[100:103], v[172:175], v[76:79]
	v_mfma_f32_16x16x32_bf16 v[72:75], v[140:143], v[172:175], v[72:75]
	s_setprio 0
	s_barrier
	s_and_b32 s29, s22, 0xffff
	s_mov_b32 s30, s10
	s_mov_b32 s31, s11
	s_mov_b32 m0, s15
	ds_read_b128 v[176:179], v217
	ds_read_b128 v[194:197], v217 offset:1024
	ds_read_b128 v[198:201], v217 offset:2048
	ds_read_b128 v[202:205], v217 offset:3072
	buffer_load_dwordx4 v211, s[28:31], 0 offen lds
	s_mov_b32 m0, s33
	s_nop 0
	buffer_load_dwordx4 v213, s[28:31], 0 offen lds
	s_barrier
	s_waitcnt lgkmcnt(0)
	s_setprio 1
	s_waitcnt lgkmcnt(3)
	v_mfma_f32_16x16x32_bf16 v[128:131], v[176:179], v[144:147], 0
	s_waitcnt lgkmcnt(1)
	v_mfma_f32_16x16x32_bf16 v[124:127], v[198:201], v[144:147], 0
	v_mfma_f32_16x16x32_bf16 v[108:111], v[176:179], v[152:155], 0
	v_mfma_f32_16x16x32_bf16 v[104:107], v[198:201], v[152:155], 0
	v_mfma_f32_16x16x32_bf16 v[84:87], v[176:179], v[160:163], 0
	v_mfma_f32_16x16x32_bf16 v[80:83], v[198:201], v[160:163], 0
	v_mfma_f32_16x16x32_bf16 v[68:71], v[176:179], v[168:171], 0
	v_mfma_f32_16x16x32_bf16 v[64:67], v[198:201], v[168:171], 0
	v_mfma_f32_16x16x32_bf16 v[128:131], v[194:197], v[148:151], v[128:131]
	s_waitcnt lgkmcnt(0)
	v_mfma_f32_16x16x32_bf16 v[124:127], v[202:205], v[148:151], v[124:127]
	v_mfma_f32_16x16x32_bf16 v[108:111], v[194:197], v[156:159], v[108:111]
	v_mfma_f32_16x16x32_bf16 v[104:107], v[202:205], v[156:159], v[104:107]
	v_mfma_f32_16x16x32_bf16 v[84:87], v[194:197], v[164:167], v[84:87]
	v_mfma_f32_16x16x32_bf16 v[80:83], v[202:205], v[164:167], v[80:83]
	v_mfma_f32_16x16x32_bf16 v[68:71], v[194:197], v[172:175], v[68:71]
	v_mfma_f32_16x16x32_bf16 v[64:67], v[202:205], v[172:175], v[64:67]
	s_setprio 0
	s_and_b32 s37, s23, 0xffff
	s_mov_b32 s38, s10
	s_mov_b32 s39, s11
	s_mov_b32 m0, s14
	s_barrier
; #define PG8_STAGE(bufoff, gbase, voff) do { const __amdgpu_buffer_rsrc_t _r = __builtin_amdgcn_make_buffer_rsrc((void*)(gbase), (short)0, 0x7fffffff, 0x00020000); _Pragma("unroll") for (int _i = 0; _i < 2; ++_i) \
;         __builtin_amdgcn_raw_ptr_buffer_load_lds(_r, (LAS unsigned*)(lds + (bufoff) + ldsw + _i * 8192), 16, (int)(voff)[_i], 0, 0, 0); } while (0)
; #define PG8_LDA(dst, b, h) do { _Pragma("unroll") for (int m = 0; m < 4; ++m) _Pragma("unroll") for (int k = 0; k < 2; ++k) dst[m][k] = *(const LAS bf16x8*)(lds + PG8_SA(b, h) + aoff + m * 2048 + k * 1024); } while (0)
; #define PG8_LDB(dst, b, h) do { _Pragma("unroll") for (int n = 0; n < 2; ++n) _Pragma("unroll") for (int k = 0; k < 2; ++k) dst[n][k] = *(const LAS bf16x8*)(lds + PG8_SB(b, h) + boff + n * 2048 + k * 1024); } while (0)
; #define PG8_MMA(ai, bj, At, Bt) do { __builtin_amdgcn_s_setprio(1); _Pragma("unroll") for (int k = 0; k < 2; ++k) _Pragma("unroll") for (int m = 0; m < 4; ++m) _Pragma("unroll") for (int n = 0; n < ((bj) == 1 ? NB1 : 2); ++n) \
;         acc[ai][bj][m][n] = __builtin_amdgcn_mfma_f32_16x16x32_bf16(Bt[n][k], At[m][k], acc[ai][bj][m][n], 0, 0, 0); __builtin_amdgcn_s_setprio(0); } while (0)
; #define PG8_WAIT_V(n) asm volatile("s_waitcnt vmcnt(" #n ")" ::: "memory")
; #define PG8_WAIT_L(n) asm volatile("s_waitcnt lgkmcnt(" #n ")" ::: "memory")
; #define PG8_BAR __builtin_amdgcn_s_barrier()
; #define PG8_SCHED __builtin_amdgcn_sched_barrier(0)
;     ...
;             PG8_WAIT_V(6); PG8_BAR; PG8_MMA(1, 1, At, B1); PG8_BAR;
;             PG8_LDB(B0, 1, 0); PG8_SCHED; PG8_LDA(At, 1, 0); PG8_STAGE(PG8_SA(0, 1), a2 + hstepA, voffA);
;             PG8_WAIT_L(8); PG8_BAR; PG8_WAIT_L(0); PG8_MMA(0, 0, At, B0); PG8_BAR; PG8_SCHED;
;             PG8_LDB(B1, 1, 1); PG8_STAGE(PG8_SB(1, 0), b3, voffB);
;             PG8_BAR; PG8_WAIT_L(0); PG8_MMA(0, 1, At, B1); PG8_BAR;
;             PG8_LDA(At, 1, 1); PG8_STAGE(PG8_SA(1, 0), a3, voffA);
;             PG8_BAR; PG8_WAIT_L(0); PG8_MMA(1, 0, At, B0); PG8_BAR; PG8_SCHED;
;             PG8_STAGE(PG8_SB(1, 1), b3 + hstepB, voffB);
;             PG8_WAIT_V(6); PG8_BAR; PG8_MMA(1, 1, At, B1); PG8_BAR;
	ds_read_b128 v[144:147], v216 offset:16384
	ds_read_b128 v[148:151], v216 offset:17408
	ds_read_b128 v[152:155], v216 offset:18432
	ds_read_b128 v[156:159], v216 offset:19456
	ds_read_b128 v[160:163], v216 offset:20480
	ds_read_b128 v[164:167], v216 offset:21504
	ds_read_b128 v[168:171], v216 offset:22528
	ds_read_b128 v[172:175], v216 offset:23552
	buffer_load_dwordx4 v210, s[36:39], 0 offen lds
	s_mov_b32 m0, s35
	s_nop 0
	buffer_load_dwordx4 v212, s[36:39], 0 offen lds
	s_barrier
	s_waitcnt lgkmcnt(0)
	s_setprio 1
	s_waitcnt lgkmcnt(7)
	v_mfma_f32_16x16x32_bf16 v[60:63], v[96:99], v[144:147], 0
	v_mfma_f32_16x16x32_bf16 v[56:59], v[136:139], v[144:147], 0
	s_waitcnt lgkmcnt(5)
	v_mfma_f32_16x16x32_bf16 v[44:47], v[96:99], v[152:155], 0
	v_mfma_f32_16x16x32_bf16 v[40:43], v[136:139], v[152:155], 0
	s_waitcnt lgkmcnt(3)
	v_mfma_f32_16x16x32_bf16 v[28:31], v[96:99], v[160:163], 0
	v_mfma_f32_16x16x32_bf16 v[24:27], v[136:139], v[160:163], 0
	s_waitcnt lgkmcnt(1)
	v_mfma_f32_16x16x32_bf16 v[12:15], v[96:99], v[168:171], 0
	v_mfma_f32_16x16x32_bf16 v[8:11], v[136:139], v[168:171], 0
	v_mfma_f32_16x16x32_bf16 v[60:63], v[100:103], v[148:151], v[60:63]
	v_mfma_f32_16x16x32_bf16 v[56:59], v[140:143], v[148:151], v[56:59]
	v_mfma_f32_16x16x32_bf16 v[44:47], v[100:103], v[156:159], v[44:47]
	v_mfma_f32_16x16x32_bf16 v[40:43], v[140:143], v[156:159], v[40:43]
	v_mfma_f32_16x16x32_bf16 v[28:31], v[100:103], v[164:167], v[28:31]
	v_mfma_f32_16x16x32_bf16 v[24:27], v[140:143], v[164:167], v[24:27]
	s_waitcnt lgkmcnt(0)
	v_mfma_f32_16x16x32_bf16 v[12:15], v[100:103], v[172:175], v[12:15]
	v_mfma_f32_16x16x32_bf16 v[8:11], v[140:143], v[172:175], v[8:11]
	s_setprio 0
	s_barrier
	s_add_u32 s8, s28, s18
	s_addc_u32 s82, s22, s19
	s_and_b32 s9, s82, 0xffff
	s_mov_b32 m0, s52
	s_nop 0
	buffer_load_dwordx4 v211, s[8:11], 0 offen lds
	s_mov_b32 m0, s53
	s_nop 0
	buffer_load_dwordx4 v213, s[8:11], 0 offen lds
	s_waitcnt vmcnt(6)
	s_barrier
	s_setprio 1
	v_mfma_f32_16x16x32_bf16 v[52:55], v[176:179], v[144:147], 0
	v_mfma_f32_16x16x32_bf16 v[48:51], v[198:201], v[144:147], 0
	v_mfma_f32_16x16x32_bf16 v[36:39], v[176:179], v[152:155], 0
	v_mfma_f32_16x16x32_bf16 v[32:35], v[198:201], v[152:155], 0
	v_mfma_f32_16x16x32_bf16 v[20:23], v[176:179], v[160:163], 0
	v_mfma_f32_16x16x32_bf16 v[16:19], v[198:201], v[160:163], 0
	v_mfma_f32_16x16x32_bf16 v[4:7], v[176:179], v[168:171], 0
	v_mfma_f32_16x16x32_bf16 v[0:3], v[198:201], v[168:171], 0
	v_mfma_f32_16x16x32_bf16 v[52:55], v[194:197], v[148:151], v[52:55]
	v_mfma_f32_16x16x32_bf16 v[48:51], v[202:205], v[148:151], v[48:51]
	v_mfma_f32_16x16x32_bf16 v[36:39], v[194:197], v[156:159], v[36:39]
	v_mfma_f32_16x16x32_bf16 v[32:35], v[202:205], v[156:159], v[32:35]
	v_mfma_f32_16x16x32_bf16 v[20:23], v[194:197], v[164:167], v[20:23]
	v_mfma_f32_16x16x32_bf16 v[16:19], v[202:205], v[164:167], v[16:19]
	v_mfma_f32_16x16x32_bf16 v[4:7], v[194:197], v[172:175], v[4:7]
	v_mfma_f32_16x16x32_bf16 v[0:3], v[202:205], v[172:175], v[0:3]
	s_setprio 0
	s_barrier
	s_branch .Lkmid_575
	.p2align 6
	s_nop 0
	s_nop 0
	s_nop 0
	s_nop 0
	s_nop 0
	s_nop 0
	s_nop 0
	s_nop 0
	s_nop 0
	s_nop 0

;     __device__ __forceinline__ size_t a_off(const Unit& u) const { return (size_t)u.pm * atile; }
;     __device__ __forceinline__ size_t b_off(const Unit& u) const { return (size_t)u.pn * btile; }
;     __device__ __forceinline__ bool next(int i, Unit& u) const { const long L = (long)i * G + c; if (L >= NG * 8) return false; u.g = (int)(L >> 3); u.pm = (int)(L & 7); u.pn = 0; return true; }
;     __device__ __forceinline__ size_t a_off(const Unit& u) const { return ((size_t)u.g * NROW + (size_t)u.pm * BM) * KA * 2; }
;     __device__ __forceinline__ size_t b_off(const Unit& u) const { return (size_t)u.g * btile; }
;     __device__ __forceinline__ bool next(int i, Unit& u) const { if (i >= 2) return false; u.g = g; u.pm = 2 * b + i; u.pn = 0; return true; }
;     __device__ __forceinline__ size_t a_off(const Unit& u) const { return ((size_t)u.g * NROW + (size_t)u.pm * BM) * KA * 2; }
;     __device__ __forceinline__ size_t b_off(const Unit& u) const { return (size_t)u.g * btile; }
; #define PG8_STAGE(bufoff, gbase, voff) do { const __amdgpu_buffer_rsrc_t _r = __builtin_amdgcn_make_buffer_rsrc((void*)(gbase), (short)0, 0x7fffffff, 0x00020000); _Pragma("unroll") for (int _i = 0; _i < 2; ++_i) \
;         __builtin_amdgcn_raw_ptr_buffer_load_lds(_r, (LAS unsigned*)(lds + (bufoff) + ldsw + _i * 8192), 16, (int)(voff)[_i], 0, 0, 0); } while (0)
; #define PG8_WAIT_L(n) asm volatile("s_waitcnt lgkmcnt(" #n ")" ::: "memory")
; #define PG8_BAR __builtin_amdgcn_s_barrier()
; #define PG8_SCHED __builtin_amdgcn_sched_barrier(0)
;     ...
;         const bool has_next = S.next(ui + 1, nxt);
;         const char* nA = has_next ? (const char*)Ap + S.a_off(nxt) : cA; const char* nB = has_next ? (const char*)Btp + S.b_off(nxt) : cB;
;         for (int t = 0; t < nt; t += 2) {
;             const bool last = (t == nt - 2);
;             const char* a1 = cA + (size_t)(t + 1) * kstep;
;             const char* a2 = last ? nA : cA + (size_t)(t + 2) * kstep; const char* b2 = last ? nB : cB + (size_t)(t + 2) * kstep;
;             const char* a3 = a2 + kstep; const char* b3 = b2 + kstep;
;             PG8_LDB(B0, 0, 0); PG8_SCHED; PG8_LDA(At, 0, 0); PG8_STAGE(PG8_SA(1, 1), a1 + hstepA, voffA);
;             PG8_WAIT_L(8); PG8_BAR; PG8_WAIT_L(0); PG8_MMA(0, 0, At, B0); PG8_BAR; PG8_SCHED;
;             PG8_LDB(B1, 0, 1); PG8_STAGE(PG8_SB(0, 0), b2, voffB);
.LBB0_625:
	s_ashr_i32 s97, s96, 31
	s_lshl_b64 s[8:9], s[96:97], 19
	s_add_u32 s68, s40, s8
	s_addc_u32 s69, s41, s9
	s_ashr_i32 s95, s94, 31
	s_lshl_b64 s[8:9], s[94:95], 19
	s_add_u32 s12, s3, s8
	v_cmp_lt_i64_e64 s[0:1], s[0:1], v[184:185]
	s_addc_u32 s13, s87, s9
	s_andn2_b64 vcc, exec, s[36:37]
	s_waitcnt lgkmcnt(0)
	s_cbranch_vccnz .Lkzero_627
	s_and_b64 s[0:1], s[0:1], exec
	s_cselect_b32 s0, s69, s27
	s_cselect_b32 s1, s68, s26
	s_cselect_b32 s47, s13, s25
	s_cselect_b32 s51, s12, s24
	s_add_u32 s89, s26, 0x100
	s_addc_u32 s90, s27, 0
	s_add_u32 s91, s24, 0x100
	s_mov_b64 s[44:45], s[36:37]
	s_addc_u32 s92, s25, 0
	s_mov_b32 s8, 0
	ds_read_b128 v[128:131], v212
	ds_read_b128 v[132:135], v212 offset:1024
	ds_read_b128 v[136:139], v212 offset:2048
	ds_read_b128 v[140:143], v212 offset:3072
	s_add_i32 s16, s8, 2
	s_cmp_eq_u32 s82, s8
	s_cselect_b32 s36, s1, s89
	s_cselect_b32 s23, s0, s90
	s_cselect_b32 s22, s47, s92
	s_cselect_b32 s28, s51, s91
	s_add_u32 s24, s36, 0x80
	s_addc_u32 s17, s23, 0
	s_add_u32 s8, s89, s18
	s_addc_u32 s9, s90, s19
	s_add_u32 s8, s8, 0xffffff80
	s_addc_u32 s9, s9, -1
	s_and_b32 s9, s9, 0xffff
	s_mov_b32 m0, s83
	ds_read_b128 v[144:147], v213
	ds_read_b128 v[148:151], v213 offset:1024
	ds_read_b128 v[152:155], v213 offset:2048
	ds_read_b128 v[156:159], v213 offset:3072
	ds_read_b128 v[160:163], v213 offset:4096
	ds_read_b128 v[164:167], v213 offset:5120
	ds_read_b128 v[168:171], v213 offset:6144
	ds_read_b128 v[172:175], v213 offset:7168
	buffer_load_dwordx4 v206, s[8:11], 0 offen lds
	s_mov_b32 m0, s84
	s_nop 0
	buffer_load_dwordx4 v208, s[8:11], 0 offen lds
	s_waitcnt lgkmcnt(8)
	s_barrier
	s_waitcnt lgkmcnt(0)
	s_setprio 1
	s_waitcnt lgkmcnt(7)
	v_mfma_f32_16x16x32_bf16 v[112:115], v[128:131], v[144:147], 0
	v_mfma_f32_16x16x32_bf16 v[116:119], v[136:139], v[144:147], 0
	s_waitcnt lgkmcnt(5)
	v_mfma_f32_16x16x32_bf16 v[100:103], v[128:131], v[152:155], 0
	v_mfma_f32_16x16x32_bf16 v[96:99], v[136:139], v[152:155], 0
	s_waitcnt lgkmcnt(3)
	v_mfma_f32_16x16x32_bf16 v[84:87], v[128:131], v[160:163], 0
	v_mfma_f32_16x16x32_bf16 v[80:83], v[136:139], v[160:163], 0
	s_waitcnt lgkmcnt(1)
	v_mfma_f32_16x16x32_bf16 v[68:71], v[128:131], v[168:171], 0
	v_mfma_f32_16x16x32_bf16 v[64:67], v[136:139], v[168:171], 0
	v_mfma_f32_16x16x32_bf16 v[112:115], v[132:135], v[148:151], v[112:115]
	v_mfma_f32_16x16x32_bf16 v[116:119], v[140:143], v[148:151], v[116:119]
	v_mfma_f32_16x16x32_bf16 v[100:103], v[132:135], v[156:159], v[100:103]
	v_mfma_f32_16x16x32_bf16 v[96:99], v[140:143], v[156:159], v[96:99]
	v_mfma_f32_16x16x32_bf16 v[84:87], v[132:135], v[164:167], v[84:87]
	v_mfma_f32_16x16x32_bf16 v[80:83], v[140:143], v[164:167], v[80:83]
	s_waitcnt lgkmcnt(0)
	v_mfma_f32_16x16x32_bf16 v[68:71], v[132:135], v[172:175], v[68:71]
	v_mfma_f32_16x16x32_bf16 v[64:67], v[140:143], v[172:175], v[64:67]
	s_setprio 0
	s_barrier
	s_and_b32 s29, s22, 0xffff
	s_mov_b32 s30, s10
	s_mov_b32 s31, s11
	s_mov_b32 m0, s15
	ds_read_b128 v[176:179], v214
	ds_read_b128 v[180:183], v214 offset:1024
	ds_read_b128 v[188:191], v214 offset:2048
	ds_read_b128 v[192:195], v214 offset:3072
	buffer_load_dwordx4 v207, s[28:31], 0 offen lds
	s_mov_b32 m0, s33
	s_nop 0
	buffer_load_dwordx4 v209, s[28:31], 0 offen lds
	s_barrier
; #define PG8_STAGE(bufoff, gbase, voff) do { const __amdgpu_buffer_rsrc_t _r = __builtin_amdgcn_make_buffer_rsrc((void*)(gbase), (short)0, 0x7fffffff, 0x00020000); _Pragma("unroll") for (int _i = 0; _i < 2; ++_i) \
;         __builtin_amdgcn_raw_ptr_buffer_load_lds(_r, (LAS unsigned*)(lds + (bufoff) + ldsw + _i * 8192), 16, (int)(voff)[_i], 0, 0, 0); } while (0)
; #define PG8_LDA(dst, b, h) do { _Pragma("unroll") for (int m = 0; m < 4; ++m) _Pragma("unroll") for (int k = 0; k < 2; ++k) dst[m][k] = *(const LAS bf16x8*)(lds + PG8_SA(b, h) + aoff + m * 2048 + k * 1024); } while (0)
; #define PG8_MMA(ai, bj, At, Bt) do { __builtin_amdgcn_s_setprio(1); _Pragma("unroll") for (int k = 0; k < 2; ++k) _Pragma("unroll") for (int m = 0; m < 4; ++m) _Pragma("unroll") for (int n = 0; n < ((bj) == 1 ? NB1 : 2); ++n) \
;         acc[ai][bj][m][n] = __builtin_amdgcn_mfma_f32_16x16x32_bf16(Bt[n][k], At[m][k], acc[ai][bj][m][n], 0, 0, 0); __builtin_amdgcn_s_setprio(0); } while (0)
; #define PG8_WAIT_V(n) asm volatile("s_waitcnt vmcnt(" #n ")" ::: "memory")
; #define PG8_WAIT_L(n) asm volatile("s_waitcnt lgkmcnt(" #n ")" ::: "memory")
; #define PG8_BAR __builtin_amdgcn_s_barrier()
; #define PG8_SCHED __builtin_amdgcn_sched_barrier(0)
;     ...
;             PG8_BAR; PG8_WAIT_L(0); PG8_MMA(0, 1, At, B1); PG8_BAR;
;             PG8_LDA(At, 0, 1); PG8_STAGE(PG8_SA(0, 0), a2, voffA);
;             PG8_BAR; PG8_WAIT_L(0); PG8_MMA(1, 0, At, B0); PG8_BAR; PG8_SCHED;
;             PG8_STAGE(PG8_SB(0, 1), b2 + hstepB, voffB);
;             PG8_WAIT_V(6); PG8_BAR; PG8_MMA(1, 1, At, B1); PG8_BAR;
	s_waitcnt lgkmcnt(0)
	s_setprio 1
	s_waitcnt lgkmcnt(3)
	v_mfma_f32_16x16x32_bf16 v[124:127], v[176:179], v[144:147], 0
	s_waitcnt lgkmcnt(1)
	v_mfma_f32_16x16x32_bf16 v[120:123], v[188:191], v[144:147], 0
	v_mfma_f32_16x16x32_bf16 v[108:111], v[176:179], v[152:155], 0
	v_mfma_f32_16x16x32_bf16 v[104:107], v[188:191], v[152:155], 0
	v_mfma_f32_16x16x32_bf16 v[92:95], v[176:179], v[160:163], 0
	v_mfma_f32_16x16x32_bf16 v[88:91], v[188:191], v[160:163], 0
	v_mfma_f32_16x16x32_bf16 v[76:79], v[176:179], v[168:171], 0
	v_mfma_f32_16x16x32_bf16 v[72:75], v[188:191], v[168:171], 0
	v_mfma_f32_16x16x32_bf16 v[124:127], v[180:183], v[148:151], v[124:127]
	s_waitcnt lgkmcnt(0)
	v_mfma_f32_16x16x32_bf16 v[120:123], v[192:195], v[148:151], v[120:123]
	v_mfma_f32_16x16x32_bf16 v[108:111], v[180:183], v[156:159], v[108:111]
	v_mfma_f32_16x16x32_bf16 v[104:107], v[192:195], v[156:159], v[104:107]
	v_mfma_f32_16x16x32_bf16 v[92:95], v[180:183], v[164:167], v[92:95]
	v_mfma_f32_16x16x32_bf16 v[88:91], v[192:195], v[164:167], v[88:91]
	v_mfma_f32_16x16x32_bf16 v[76:79], v[180:183], v[172:175], v[76:79]
	v_mfma_f32_16x16x32_bf16 v[72:75], v[192:195], v[172:175], v[72:75]
	s_setprio 0
	s_and_b32 s37, s23, 0xffff
	s_mov_b32 s38, s10
	s_mov_b32 s39, s11
	s_mov_b32 m0, s14
	s_barrier
	ds_read_b128 v[144:147], v213 offset:16384
	ds_read_b128 v[148:151], v213 offset:17408
	ds_read_b128 v[152:155], v213 offset:18432
	ds_read_b128 v[156:159], v213 offset:19456
	ds_read_b128 v[160:163], v213 offset:20480
	ds_read_b128 v[164:167], v213 offset:21504
	ds_read_b128 v[168:171], v213 offset:22528
	ds_read_b128 v[172:175], v213 offset:23552
	buffer_load_dwordx4 v206, s[36:39], 0 offen lds
	s_mov_b32 m0, s35
	s_nop 0
	buffer_load_dwordx4 v208, s[36:39], 0 offen lds
	s_barrier
	s_waitcnt lgkmcnt(0)
	s_setprio 1
	s_waitcnt lgkmcnt(7)
	v_mfma_f32_16x16x32_bf16 v[52:55], v[128:131], v[144:147], 0
	v_mfma_f32_16x16x32_bf16 v[48:51], v[136:139], v[144:147], 0
	s_waitcnt lgkmcnt(5)
	v_mfma_f32_16x16x32_bf16 v[36:39], v[128:131], v[152:155], 0
	v_mfma_f32_16x16x32_bf16 v[32:35], v[136:139], v[152:155], 0
	s_waitcnt lgkmcnt(3)
	v_mfma_f32_16x16x32_bf16 v[20:23], v[128:131], v[160:163], 0
	v_mfma_f32_16x16x32_bf16 v[16:19], v[136:139], v[160:163], 0
	s_waitcnt lgkmcnt(1)
	v_mfma_f32_16x16x32_bf16 v[4:7], v[128:131], v[168:171], 0
	v_mfma_f32_16x16x32_bf16 v[0:3], v[136:139], v[168:171], 0
	v_mfma_f32_16x16x32_bf16 v[52:55], v[132:135], v[148:151], v[52:55]
	v_mfma_f32_16x16x32_bf16 v[48:51], v[140:143], v[148:151], v[48:51]
	v_mfma_f32_16x16x32_bf16 v[36:39], v[132:135], v[156:159], v[36:39]
	v_mfma_f32_16x16x32_bf16 v[32:35], v[140:143], v[156:159], v[32:35]
	v_mfma_f32_16x16x32_bf16 v[20:23], v[132:135], v[164:167], v[20:23]
	v_mfma_f32_16x16x32_bf16 v[16:19], v[140:143], v[164:167], v[16:19]
	s_waitcnt lgkmcnt(0)
	v_mfma_f32_16x16x32_bf16 v[4:7], v[132:135], v[172:175], v[4:7]
	v_mfma_f32_16x16x32_bf16 v[0:3], v[140:143], v[172:175], v[0:3]
	s_setprio 0
	s_barrier
	s_add_u32 s8, s28, s42
	s_addc_u32 s93, s22, s43
	s_and_b32 s9, s93, 0xffff
	s_mov_b32 m0, s65
	s_nop 0
	buffer_load_dwordx4 v207, s[8:11], 0 offen lds
	s_mov_b32 m0, s67
	s_nop 0
	buffer_load_dwordx4 v209, s[8:11], 0 offen lds
	s_waitcnt vmcnt(6)
	s_barrier
	s_setprio 1
	v_mfma_f32_16x16x32_bf16 v[60:63], v[176:179], v[144:147], 0
	v_mfma_f32_16x16x32_bf16 v[56:59], v[188:191], v[144:147], 0
	v_mfma_f32_16x16x32_bf16 v[44:47], v[176:179], v[152:155], 0
	v_mfma_f32_16x16x32_bf16 v[40:43], v[188:191], v[152:155], 0
	v_mfma_f32_16x16x32_bf16 v[28:31], v[176:179], v[160:163], 0
	v_mfma_f32_16x16x32_bf16 v[24:27], v[188:191], v[160:163], 0
	v_mfma_f32_16x16x32_bf16 v[12:15], v[176:179], v[168:171], 0
	v_mfma_f32_16x16x32_bf16 v[8:11], v[188:191], v[168:171], 0
	v_mfma_f32_16x16x32_bf16 v[60:63], v[180:183], v[148:151], v[60:63]
	v_mfma_f32_16x16x32_bf16 v[56:59], v[192:195], v[148:151], v[56:59]
	v_mfma_f32_16x16x32_bf16 v[44:47], v[180:183], v[156:159], v[44:47]
	v_mfma_f32_16x16x32_bf16 v[40:43], v[192:195], v[156:159], v[40:43]
	v_mfma_f32_16x16x32_bf16 v[28:31], v[180:183], v[164:167], v[28:31]
	v_mfma_f32_16x16x32_bf16 v[24:27], v[192:195], v[164:167], v[24:27]
	v_mfma_f32_16x16x32_bf16 v[12:15], v[180:183], v[172:175], v[12:15]
	v_mfma_f32_16x16x32_bf16 v[8:11], v[192:195], v[172:175], v[8:11]
	s_setprio 0
	s_barrier
	s_branch .Lkmid_627
	.p2align 6
	s_nop 0
	s_nop 0
	s_nop 0
	s_nop 0
	s_nop 0
	s_nop 0
	s_nop 0
	s_nop 0
	s_nop 0
	s_nop 0

;     __device__ __forceinline__ size_t a_off(const Unit& u) const { return (size_t)u.pm * atile; }
;     __device__ __forceinline__ size_t b_off(const Unit& u) const { return (size_t)u.pn * btile; }
;     __device__ __forceinline__ bool next(int i, Unit& u) const { const long L = (long)i * G + c; if (L >= NG * 8) return false; u.g = (int)(L >> 3); u.pm = (int)(L & 7); u.pn = 0; return true; }
;     __device__ __forceinline__ size_t a_off(const Unit& u) const { return ((size_t)u.g * NROW + (size_t)u.pm * BM) * KA * 2; }
;     __device__ __forceinline__ size_t b_off(const Unit& u) const { return (size_t)u.g * btile; }
;     __device__ __forceinline__ bool next(int i, Unit& u) const { if (i >= 2) return false; u.g = g; u.pm = 2 * b + i; u.pn = 0; return true; }
;     __device__ __forceinline__ size_t a_off(const Unit& u) const { return ((size_t)u.g * NROW + (size_t)u.pm * BM) * KA * 2; }
;     __device__ __forceinline__ size_t b_off(const Unit& u) const { return (size_t)u.g * btile; }
; #define PG8_STAGE(bufoff, gbase, voff) do { const __amdgpu_buffer_rsrc_t _r = __builtin_amdgcn_make_buffer_rsrc((void*)(gbase), (short)0, 0x7fffffff, 0x00020000); _Pragma("unroll") for (int _i = 0; _i < 2; ++_i) \
;         __builtin_amdgcn_raw_ptr_buffer_load_lds(_r, (LAS unsigned*)(lds + (bufoff) + ldsw + _i * 8192), 16, (int)(voff)[_i], 0, 0, 0); } while (0)
; #define PG8_WAIT_L(n) asm volatile("s_waitcnt lgkmcnt(" #n ")" ::: "memory")
; #define PG8_BAR __builtin_amdgcn_s_barrier()
; #define PG8_SCHED __builtin_amdgcn_sched_barrier(0)
;     ...
;         const bool has_next = S.next(ui + 1, nxt);
;         const char* nA = has_next ? (const char*)Ap + S.a_off(nxt) : cA; const char* nB = has_next ? (const char*)Btp + S.b_off(nxt) : cB;
;         for (int t = 0; t < nt; t += 2) {
;             const bool last = (t == nt - 2);
;             const char* a1 = cA + (size_t)(t + 1) * kstep;
;             const char* a2 = last ? nA : cA + (size_t)(t + 2) * kstep; const char* b2 = last ? nB : cB + (size_t)(t + 2) * kstep;
;             const char* a3 = a2 + kstep; const char* b3 = b2 + kstep;
;             PG8_LDB(B0, 0, 0); PG8_SCHED; PG8_LDA(At, 0, 0); PG8_STAGE(PG8_SA(1, 1), a1 + hstepA, voffA);
;             PG8_WAIT_L(8); PG8_BAR; PG8_WAIT_L(0); PG8_MMA(0, 0, At, B0); PG8_BAR; PG8_SCHED;
;             PG8_LDB(B1, 0, 1); PG8_STAGE(PG8_SB(0, 0), b2, voffB);
.Lnext_done_17625:
.LBB0_688:
	s_ashr_i32 s59, s58, 31
	s_lshl_b64 s[16:17], s[58:59], 19
	s_add_u32 s64, s20, s16
	s_addc_u32 s65, s21, s17
	s_ashr_i32 s53, s52, 31
	s_lshl_b64 s[16:17], s[52:53], 19
	s_add_u32 s66, s76, s16
	v_cmp_lt_i64_e64 s[12:13], s[12:13], v[170:171]
	s_addc_u32 s67, s77, s17
	s_andn2_b64 vcc, exec, s[50:51]
	s_cbranch_vccnz .Lkzero_690
	s_and_b64 s[16:17], s[12:13], exec
	s_cselect_b32 s53, s65, s27
	s_cselect_b32 s59, s64, s26
	s_cselect_b32 s96, s67, s25
	s_cselect_b32 s97, s66, s24
	s_add_u32 vcc_lo, s26, 0x100
	s_addc_u32 vcc_hi, s27, 0
	s_add_u32 s3, s24, 0x100
	s_addc_u32 s46, s25, 0
	s_mov_b32 s16, 0
	ds_read_b128 v[76:79], v193
	ds_read_b128 v[88:91], v193 offset:1024
	ds_read_b128 v[92:95], v193 offset:2048
	ds_read_b128 v[128:131], v193 offset:3072
	s_add_i32 s22, s16, 2
	s_cmp_eq_u32 s91, s16
	s_cselect_b32 s36, s59, vcc_lo
	s_cselect_b32 s26, s53, vcc_hi
	s_cselect_b32 s25, s96, s46
	s_cselect_b32 s28, s97, s3
	s_add_u32 s24, s36, 0x80
	s_addc_u32 s23, s26, 0
	s_add_u32 s16, vcc_lo, s0
	s_addc_u32 s17, vcc_hi, s1
	s_add_u32 s16, s16, 0xffffff80
	s_addc_u32 s17, s17, -1
	s_and_b32 s17, s17, 0xffff
	s_mov_b32 m0, s92
	ds_read_b128 v[132:135], v194
	ds_read_b128 v[136:139], v194 offset:1024
	ds_read_b128 v[140:143], v194 offset:2048
	ds_read_b128 v[174:177], v194 offset:3072
	ds_read_b128 v[178:181], v194 offset:4096
	ds_read_b128 v[182:185], v194 offset:5120
	ds_read_b128 v[202:205], v194 offset:6144
	ds_read_b128 v[206:209], v194 offset:7168
	buffer_load_dwordx4 v186, s[16:19], 0 offen lds
	s_mov_b32 m0, s93
	s_nop 0
	buffer_load_dwordx4 v188, s[16:19], 0 offen lds
	s_waitcnt lgkmcnt(8)
	s_barrier
	s_waitcnt lgkmcnt(0)
	s_setprio 1
	s_waitcnt lgkmcnt(7)
	v_mfma_f32_16x16x32_bf16 v[152:155], v[76:79], v[132:135], 0
	v_mfma_f32_16x16x32_bf16 v[144:147], v[92:95], v[132:135], 0
	s_waitcnt lgkmcnt(5)
	v_mfma_f32_16x16x32_bf16 v[124:127], v[76:79], v[140:143], 0
	v_mfma_f32_16x16x32_bf16 v[120:123], v[92:95], v[140:143], 0
	s_waitcnt lgkmcnt(3)
	v_mfma_f32_16x16x32_bf16 v[108:111], v[76:79], v[178:181], 0
	v_mfma_f32_16x16x32_bf16 v[104:107], v[92:95], v[178:181], 0
	s_waitcnt lgkmcnt(1)
	v_mfma_f32_16x16x32_bf16 v[84:87], v[76:79], v[202:205], 0
	v_mfma_f32_16x16x32_bf16 v[80:83], v[92:95], v[202:205], 0
	v_mfma_f32_16x16x32_bf16 v[152:155], v[88:91], v[136:139], v[152:155]
	v_mfma_f32_16x16x32_bf16 v[144:147], v[128:131], v[136:139], v[144:147]
	v_mfma_f32_16x16x32_bf16 v[124:127], v[88:91], v[174:177], v[124:127]
	v_mfma_f32_16x16x32_bf16 v[120:123], v[128:131], v[174:177], v[120:123]
	v_mfma_f32_16x16x32_bf16 v[108:111], v[88:91], v[182:185], v[108:111]
	v_mfma_f32_16x16x32_bf16 v[104:107], v[128:131], v[182:185], v[104:107]
	s_waitcnt lgkmcnt(0)
	v_mfma_f32_16x16x32_bf16 v[84:87], v[88:91], v[206:209], v[84:87]
	v_mfma_f32_16x16x32_bf16 v[80:83], v[128:131], v[206:209], v[80:83]
	s_setprio 0
	s_barrier
	s_and_b32 s29, s25, 0xffff
	s_mov_b32 s30, s18
	s_mov_b32 s31, s19
	s_mov_b32 m0, s73
	ds_read_b128 v[210:213], v195
	ds_read_b128 v[214:217], v195 offset:1024
	ds_read_b128 v[218:221], v195 offset:2048
	ds_read_b128 v[222:225], v195 offset:3072
	buffer_load_dwordx4 v187, s[28:31], 0 offen lds
	s_mov_b32 m0, s78
	s_nop 0
	buffer_load_dwordx4 v189, s[28:31], 0 offen lds
	s_barrier
; #define PG8_STAGE(bufoff, gbase, voff) do { const __amdgpu_buffer_rsrc_t _r = __builtin_amdgcn_make_buffer_rsrc((void*)(gbase), (short)0, 0x7fffffff, 0x00020000); _Pragma("unroll") for (int _i = 0; _i < 2; ++_i) \
;         __builtin_amdgcn_raw_ptr_buffer_load_lds(_r, (LAS unsigned*)(lds + (bufoff) + ldsw + _i * 8192), 16, (int)(voff)[_i], 0, 0, 0); } while (0)
; #define PG8_LDA(dst, b, h) do { _Pragma("unroll") for (int m = 0; m < 4; ++m) _Pragma("unroll") for (int k = 0; k < 2; ++k) dst[m][k] = *(const LAS bf16x8*)(lds + PG8_SA(b, h) + aoff + m * 2048 + k * 1024); } while (0)
; #define PG8_MMA(ai, bj, At, Bt) do { __builtin_amdgcn_s_setprio(1); _Pragma("unroll") for (int k = 0; k < 2; ++k) _Pragma("unroll") for (int m = 0; m < 4; ++m) _Pragma("unroll") for (int n = 0; n < ((bj) == 1 ? NB1 : 2); ++n) \
;         acc[ai][bj][m][n] = __builtin_amdgcn_mfma_f32_16x16x32_bf16(Bt[n][k], At[m][k], acc[ai][bj][m][n], 0, 0, 0); __builtin_amdgcn_s_setprio(0); } while (0)
; #define PG8_WAIT_V(n) asm volatile("s_waitcnt vmcnt(" #n ")" ::: "memory")
; #define PG8_WAIT_L(n) asm volatile("s_waitcnt lgkmcnt(" #n ")" ::: "memory")
; #define PG8_BAR __builtin_amdgcn_s_barrier()
; #define PG8_SCHED __builtin_amdgcn_sched_barrier(0)
;     ...
;             PG8_BAR; PG8_WAIT_L(0); PG8_MMA(0, 1, At, B1); PG8_BAR;
;             PG8_LDA(At, 0, 1); PG8_STAGE(PG8_SA(0, 0), a2, voffA);
;             PG8_BAR; PG8_WAIT_L(0); PG8_MMA(1, 0, At, B0); PG8_BAR; PG8_SCHED;
;             PG8_STAGE(PG8_SB(0, 1), b2 + hstepB, voffB);
;             PG8_WAIT_V(6); PG8_BAR; PG8_MMA(1, 1, At, B1); PG8_BAR;
	s_waitcnt lgkmcnt(0)
	s_setprio 1
	s_waitcnt lgkmcnt(3)
	v_mfma_f32_16x16x32_bf16 v[116:119], v[210:213], v[140:143], 0
	s_waitcnt lgkmcnt(1)
	v_mfma_f32_16x16x32_bf16 v[112:115], v[218:221], v[140:143], 0
	v_mfma_f32_16x16x32_bf16 v[100:103], v[210:213], v[178:181], 0
	v_mfma_f32_16x16x32_bf16 v[96:99], v[218:221], v[178:181], 0
	v_mfma_f32_16x16x32_bf16 v[68:71], v[210:213], v[202:205], 0
	v_mfma_f32_16x16x32_bf16 v[64:67], v[218:221], v[202:205], 0
	v_mfma_f32_16x16x32_bf16 v[156:159], v[210:213], v[132:135], 0
	v_mfma_f32_16x16x32_bf16 v[132:135], v[218:221], v[132:135], 0
	v_mfma_f32_16x16x32_bf16 v[116:119], v[214:217], v[174:177], v[116:119]
	s_waitcnt lgkmcnt(0)
	v_mfma_f32_16x16x32_bf16 v[112:115], v[222:225], v[174:177], v[112:115]
	v_mfma_f32_16x16x32_bf16 v[100:103], v[214:217], v[182:185], v[100:103]
	v_mfma_f32_16x16x32_bf16 v[96:99], v[222:225], v[182:185], v[96:99]
	v_mfma_f32_16x16x32_bf16 v[68:71], v[214:217], v[206:209], v[68:71]
	v_mfma_f32_16x16x32_bf16 v[64:67], v[222:225], v[206:209], v[64:67]
	v_mfma_f32_16x16x32_bf16 v[140:143], v[214:217], v[136:139], v[156:159]
	v_mfma_f32_16x16x32_bf16 v[132:135], v[222:225], v[136:139], v[132:135]
	s_setprio 0
	s_and_b32 s37, s26, 0xffff
	s_mov_b32 s38, s18
	s_mov_b32 s39, s19
	s_mov_b32 m0, s71
	s_barrier
	ds_read_b128 v[136:139], v194 offset:16384
	ds_read_b128 v[148:151], v194 offset:17408
	ds_read_b128 v[156:159], v194 offset:18432
	ds_read_b128 v[174:177], v194 offset:19456
	ds_read_b128 v[178:181], v194 offset:20480
	ds_read_b128 v[182:185], v194 offset:21504
	ds_read_b128 v[202:205], v194 offset:22528
	ds_read_b128 v[206:209], v194 offset:23552
	buffer_load_dwordx4 v186, s[36:39], 0 offen lds
	s_mov_b32 m0, s79
	s_nop 0
	buffer_load_dwordx4 v188, s[36:39], 0 offen lds
	s_barrier
	s_waitcnt lgkmcnt(0)
	s_setprio 1
	s_waitcnt lgkmcnt(7)
	v_mfma_f32_16x16x32_bf16 v[60:63], v[76:79], v[136:139], 0
	v_mfma_f32_16x16x32_bf16 v[52:55], v[92:95], v[136:139], 0
	s_waitcnt lgkmcnt(5)
	v_mfma_f32_16x16x32_bf16 v[44:47], v[76:79], v[156:159], 0
	v_mfma_f32_16x16x32_bf16 v[40:43], v[92:95], v[156:159], 0
	s_waitcnt lgkmcnt(3)
	v_mfma_f32_16x16x32_bf16 v[28:31], v[76:79], v[178:181], 0
	v_mfma_f32_16x16x32_bf16 v[24:27], v[92:95], v[178:181], 0
	s_waitcnt lgkmcnt(1)
	v_mfma_f32_16x16x32_bf16 v[12:15], v[76:79], v[202:205], 0
	v_mfma_f32_16x16x32_bf16 v[8:11], v[92:95], v[202:205], 0
	v_mfma_f32_16x16x32_bf16 v[60:63], v[88:91], v[148:151], v[60:63]
	v_mfma_f32_16x16x32_bf16 v[52:55], v[128:131], v[148:151], v[52:55]
	v_mfma_f32_16x16x32_bf16 v[44:47], v[88:91], v[174:177], v[44:47]
	v_mfma_f32_16x16x32_bf16 v[40:43], v[128:131], v[174:177], v[40:43]
	v_mfma_f32_16x16x32_bf16 v[28:31], v[88:91], v[182:185], v[28:31]
	v_mfma_f32_16x16x32_bf16 v[24:27], v[128:131], v[182:185], v[24:27]
	s_waitcnt lgkmcnt(0)
	v_mfma_f32_16x16x32_bf16 v[12:15], v[88:91], v[206:209], v[12:15]
	v_mfma_f32_16x16x32_bf16 v[8:11], v[128:131], v[206:209], v[8:11]
	s_setprio 0
	s_barrier
	s_add_u32 s16, s28, s44
	s_addc_u32 s74, s25, s45
	s_and_b32 s17, s74, 0xffff
	s_mov_b32 m0, s80
	s_nop 0
	buffer_load_dwordx4 v187, s[16:19], 0 offen lds
	s_mov_b32 m0, s81
	s_nop 0
	buffer_load_dwordx4 v189, s[16:19], 0 offen lds
	s_waitcnt vmcnt(6)
	s_barrier
	s_setprio 1
	v_mfma_f32_16x16x32_bf16 v[56:59], v[210:213], v[136:139], 0
	v_mfma_f32_16x16x32_bf16 v[48:51], v[218:221], v[136:139], 0
	v_mfma_f32_16x16x32_bf16 v[36:39], v[210:213], v[156:159], 0
	v_mfma_f32_16x16x32_bf16 v[32:35], v[218:221], v[156:159], 0
	v_mfma_f32_16x16x32_bf16 v[20:23], v[210:213], v[178:181], 0
	v_mfma_f32_16x16x32_bf16 v[16:19], v[218:221], v[178:181], 0
	v_mfma_f32_16x16x32_bf16 v[4:7], v[210:213], v[202:205], 0
	v_mfma_f32_16x16x32_bf16 v[0:3], v[218:221], v[202:205], 0
	v_mfma_f32_16x16x32_bf16 v[56:59], v[214:217], v[148:151], v[56:59]
	v_mfma_f32_16x16x32_bf16 v[48:51], v[222:225], v[148:151], v[48:51]
	v_mfma_f32_16x16x32_bf16 v[36:39], v[214:217], v[174:177], v[36:39]
	v_mfma_f32_16x16x32_bf16 v[32:35], v[222:225], v[174:177], v[32:35]
	v_mfma_f32_16x16x32_bf16 v[20:23], v[214:217], v[182:185], v[20:23]
	v_mfma_f32_16x16x32_bf16 v[16:19], v[222:225], v[182:185], v[16:19]
	v_mfma_f32_16x16x32_bf16 v[4:7], v[214:217], v[206:209], v[4:7]
	v_mfma_f32_16x16x32_bf16 v[0:3], v[222:225], v[206:209], v[0:3]
	s_setprio 0
	s_barrier
	s_branch .Lkmid_690
	.p2align 6
	s_nop 0
	s_nop 0
	s_nop 0
	s_nop 0
	s_nop 0
	s_nop 0
	s_nop 0
	s_nop 0
	s_nop 0
	s_nop 0

; #define PG8_STAGE(bufoff, gbase, voff) do { const __amdgpu_buffer_rsrc_t _r = __builtin_amdgcn_make_buffer_rsrc((void*)(gbase), (short)0, 0x7fffffff, 0x00020000); _Pragma("unroll") for (int _i = 0; _i < 2; ++_i) \
;         __builtin_amdgcn_raw_ptr_buffer_load_lds(_r, (LAS unsigned*)(lds + (bufoff) + ldsw + _i * 8192), 16, (int)(voff)[_i], 0, 0, 0); } while (0)
; #define PG8_LDA(dst, b, h) do { _Pragma("unroll") for (int m = 0; m < 4; ++m) _Pragma("unroll") for (int k = 0; k < 2; ++k) dst[m][k] = *(const LAS bf16x8*)(lds + PG8_SA(b, h) + aoff + m * 2048 + k * 1024); } while (0)
; #define PG8_LDB(dst, b, h) do { _Pragma("unroll") for (int n = 0; n < 2; ++n) _Pragma("unroll") for (int k = 0; k < 2; ++k) dst[n][k] = *(const LAS bf16x8*)(lds + PG8_SB(b, h) + boff + n * 2048 + k * 1024); } while (0)
; #define PG8_MMA(ai, bj, At, Bt) do { __builtin_amdgcn_s_setprio(1); _Pragma("unroll") for (int k = 0; k < 2; ++k) _Pragma("unroll") for (int m = 0; m < 4; ++m) _Pragma("unroll") for (int n = 0; n < ((bj) == 1 ? NB1 : 2); ++n) \
;         acc[ai][bj][m][n] = __builtin_amdgcn_mfma_f32_16x16x32_bf16(Bt[n][k], At[m][k], acc[ai][bj][m][n], 0, 0, 0); __builtin_amdgcn_s_setprio(0); } while (0)
; #define PG8_WAIT_L(n) asm volatile("s_waitcnt lgkmcnt(" #n ")" ::: "memory")
; #define PG8_BAR __builtin_amdgcn_s_barrier()
; #define PG8_SCHED __builtin_amdgcn_sched_barrier(0)
;     ...
;             const bool last = (t == nt - 2);
;             const char* a1 = cA + (size_t)(t + 1) * kstep;
;             const char* a2 = last ? nA : cA + (size_t)(t + 2) * kstep; const char* b2 = last ? nB : cB + (size_t)(t + 2) * kstep;
;             const char* a3 = a2 + kstep; const char* b3 = b2 + kstep;
;             PG8_LDB(B0, 0, 0); PG8_SCHED; PG8_LDA(At, 0, 0); PG8_STAGE(PG8_SA(1, 1), a1 + hstepA, voffA);
;             PG8_WAIT_L(8); PG8_BAR; PG8_WAIT_L(0); PG8_MMA(0, 0, At, B0); PG8_BAR; PG8_SCHED;
;             PG8_LDB(B1, 0, 1); PG8_STAGE(PG8_SB(0, 0), b2, voffB);
;             PG8_BAR; PG8_WAIT_L(0); PG8_MMA(0, 1, At, B1); PG8_BAR;
.LBB0_770:
	s_andn2_b64 vcc, exec, s[46:47]
	s_waitcnt lgkmcnt(0)
	s_cbranch_vccnz .Lkzero_772
	s_add_u32 s89, s18, 0x100
	s_addc_u32 s90, s19, 0
	s_add_u32 s91, s16, 0x100
	s_addc_u32 s92, s17, 0
	s_mov_b32 s8, 0
	ds_read_b128 v[128:131], v227
	ds_read_b128 v[132:135], v227 offset:1024
	ds_read_b128 v[136:139], v227 offset:2048
	ds_read_b128 v[140:143], v227 offset:3072
	s_add_i32 s22, s8, 2
	s_cmp_eq_u32 s81, s8
	s_cselect_b32 s28, s0, s89
	s_cselect_b32 s19, s1, s90
	s_cselect_b32 s18, s51, s92
	s_cselect_b32 s24, s50, s91
	s_add_u32 s16, s28, 0x80
	s_addc_u32 s17, s19, 0
	s_add_u32 s8, s89, s36
	s_addc_u32 s9, s90, s37
	s_add_u32 s8, s8, 0xffffff80
	s_addc_u32 s9, s9, -1
	s_and_b32 s9, s9, 0xffff
	s_mov_b32 m0, s82
	ds_read_b128 v[144:147], v228
	ds_read_b128 v[148:151], v228 offset:1024
	ds_read_b128 v[152:155], v228 offset:2048
	ds_read_b128 v[156:159], v228 offset:3072
	ds_read_b128 v[160:163], v228 offset:4096
	ds_read_b128 v[164:167], v228 offset:5120
	ds_read_b128 v[168:171], v228 offset:6144
	ds_read_b128 v[172:175], v228 offset:7168
	buffer_load_dwordx4 v222, s[8:11], 0 offen lds
	s_mov_b32 m0, s83
	s_nop 0
	buffer_load_dwordx4 v224, s[8:11], 0 offen lds
	s_waitcnt lgkmcnt(8)
	s_barrier
	s_waitcnt lgkmcnt(0)
	s_setprio 1
	s_waitcnt lgkmcnt(7)
	v_mfma_f32_16x16x32_bf16 v[120:123], v[128:131], v[144:147], 0
	v_mfma_f32_16x16x32_bf16 v[124:127], v[136:139], v[144:147], 0
	s_waitcnt lgkmcnt(5)
	v_mfma_f32_16x16x32_bf16 v[108:111], v[128:131], v[152:155], 0
	v_mfma_f32_16x16x32_bf16 v[104:107], v[136:139], v[152:155], 0
	s_waitcnt lgkmcnt(3)
	v_mfma_f32_16x16x32_bf16 v[92:95], v[128:131], v[160:163], 0
	v_mfma_f32_16x16x32_bf16 v[88:91], v[136:139], v[160:163], 0
	s_waitcnt lgkmcnt(1)
	v_mfma_f32_16x16x32_bf16 v[76:79], v[128:131], v[168:171], 0
	v_mfma_f32_16x16x32_bf16 v[72:75], v[136:139], v[168:171], 0
	v_mfma_f32_16x16x32_bf16 v[120:123], v[132:135], v[148:151], v[120:123]
	v_mfma_f32_16x16x32_bf16 v[124:127], v[140:143], v[148:151], v[124:127]
	v_mfma_f32_16x16x32_bf16 v[108:111], v[132:135], v[156:159], v[108:111]
	v_mfma_f32_16x16x32_bf16 v[104:107], v[140:143], v[156:159], v[104:107]
	v_mfma_f32_16x16x32_bf16 v[92:95], v[132:135], v[164:167], v[92:95]
	v_mfma_f32_16x16x32_bf16 v[88:91], v[140:143], v[164:167], v[88:91]
	s_waitcnt lgkmcnt(0)
	v_mfma_f32_16x16x32_bf16 v[76:79], v[132:135], v[172:175], v[76:79]
	v_mfma_f32_16x16x32_bf16 v[72:75], v[140:143], v[172:175], v[72:75]
	s_setprio 0
	s_barrier
	s_and_b32 s25, s18, 0xffff
	s_mov_b32 s26, s10
	s_mov_b32 s27, s11
	s_mov_b32 m0, s64
	ds_read_b128 v[176:179], v229
	ds_read_b128 v[180:183], v229 offset:1024
	ds_read_b128 v[192:195], v229 offset:2048
	ds_read_b128 v[196:199], v229 offset:3072
	buffer_load_dwordx4 v223, s[24:27], 0 offen lds
	s_mov_b32 m0, s65
	s_nop 0
	buffer_load_dwordx4 v225, s[24:27], 0 offen lds
	s_barrier
	s_waitcnt lgkmcnt(0)
	s_setprio 1
	s_waitcnt lgkmcnt(3)
	v_mfma_f32_16x16x32_bf16 v[116:119], v[176:179], v[144:147], 0
	s_waitcnt lgkmcnt(1)
	v_mfma_f32_16x16x32_bf16 v[112:115], v[192:195], v[144:147], 0
	v_mfma_f32_16x16x32_bf16 v[100:103], v[176:179], v[152:155], 0
	v_mfma_f32_16x16x32_bf16 v[96:99], v[192:195], v[152:155], 0
	v_mfma_f32_16x16x32_bf16 v[84:87], v[176:179], v[160:163], 0
	v_mfma_f32_16x16x32_bf16 v[80:83], v[192:195], v[160:163], 0
	v_mfma_f32_16x16x32_bf16 v[68:71], v[176:179], v[168:171], 0
	v_mfma_f32_16x16x32_bf16 v[64:67], v[192:195], v[168:171], 0
	v_mfma_f32_16x16x32_bf16 v[116:119], v[180:183], v[148:151], v[116:119]
	s_waitcnt lgkmcnt(0)
	v_mfma_f32_16x16x32_bf16 v[112:115], v[196:199], v[148:151], v[112:115]
	v_mfma_f32_16x16x32_bf16 v[100:103], v[180:183], v[156:159], v[100:103]
	v_mfma_f32_16x16x32_bf16 v[96:99], v[196:199], v[156:159], v[96:99]
	v_mfma_f32_16x16x32_bf16 v[84:87], v[180:183], v[164:167], v[84:87]
	v_mfma_f32_16x16x32_bf16 v[80:83], v[196:199], v[164:167], v[80:83]
	v_mfma_f32_16x16x32_bf16 v[68:71], v[180:183], v[172:175], v[68:71]
	v_mfma_f32_16x16x32_bf16 v[64:67], v[196:199], v[172:175], v[64:67]
	s_setprio 0
	s_and_b32 s29, s19, 0xffff
	s_mov_b32 s30, s10
	s_mov_b32 s31, s11
	s_mov_b32 m0, s59
	s_barrier
; #define PG8_STAGE(bufoff, gbase, voff) do { const __amdgpu_buffer_rsrc_t _r = __builtin_amdgcn_make_buffer_rsrc((void*)(gbase), (short)0, 0x7fffffff, 0x00020000); _Pragma("unroll") for (int _i = 0; _i < 2; ++_i) \
;         __builtin_amdgcn_raw_ptr_buffer_load_lds(_r, (LAS unsigned*)(lds + (bufoff) + ldsw + _i * 8192), 16, (int)(voff)[_i], 0, 0, 0); } while (0)
; #define PG8_LDA(dst, b, h) do { _Pragma("unroll") for (int m = 0; m < 4; ++m) _Pragma("unroll") for (int k = 0; k < 2; ++k) dst[m][k] = *(const LAS bf16x8*)(lds + PG8_SA(b, h) + aoff + m * 2048 + k * 1024); } while (0)
; #define PG8_MMA(ai, bj, At, Bt) do { __builtin_amdgcn_s_setprio(1); _Pragma("unroll") for (int k = 0; k < 2; ++k) _Pragma("unroll") for (int m = 0; m < 4; ++m) _Pragma("unroll") for (int n = 0; n < ((bj) == 1 ? NB1 : 2); ++n) \
;         acc[ai][bj][m][n] = __builtin_amdgcn_mfma_f32_16x16x32_bf16(Bt[n][k], At[m][k], acc[ai][bj][m][n], 0, 0, 0); __builtin_amdgcn_s_setprio(0); } while (0)
; #define PG8_WAIT_V(n) asm volatile("s_waitcnt vmcnt(" #n ")" ::: "memory")
; #define PG8_WAIT_L(n) asm volatile("s_waitcnt lgkmcnt(" #n ")" ::: "memory")
; #define PG8_BAR __builtin_amdgcn_s_barrier()
; #define PG8_SCHED __builtin_amdgcn_sched_barrier(0)
;     ...
;             PG8_LDA(At, 0, 1); PG8_STAGE(PG8_SA(0, 0), a2, voffA);
;             PG8_BAR; PG8_WAIT_L(0); PG8_MMA(1, 0, At, B0); PG8_BAR; PG8_SCHED;
;             PG8_STAGE(PG8_SB(0, 1), b2 + hstepB, voffB);
;             PG8_WAIT_V(6); PG8_BAR; PG8_MMA(1, 1, At, B1); PG8_BAR;
	ds_read_b128 v[144:147], v228 offset:16384
	ds_read_b128 v[148:151], v228 offset:17408
	ds_read_b128 v[152:155], v228 offset:18432
	ds_read_b128 v[156:159], v228 offset:19456
	ds_read_b128 v[160:163], v228 offset:20480
	ds_read_b128 v[164:167], v228 offset:21504
	ds_read_b128 v[168:171], v228 offset:22528
	ds_read_b128 v[172:175], v228 offset:23552
	buffer_load_dwordx4 v222, s[28:31], 0 offen lds
	s_mov_b32 m0, s67
	s_nop 0
	buffer_load_dwordx4 v224, s[28:31], 0 offen lds
	s_barrier
	s_waitcnt lgkmcnt(0)
	s_setprio 1
	s_waitcnt lgkmcnt(7)
	v_mfma_f32_16x16x32_bf16 v[60:63], v[128:131], v[144:147], 0
	v_mfma_f32_16x16x32_bf16 v[56:59], v[136:139], v[144:147], 0
	s_waitcnt lgkmcnt(5)
	v_mfma_f32_16x16x32_bf16 v[44:47], v[128:131], v[152:155], 0
	v_mfma_f32_16x16x32_bf16 v[40:43], v[136:139], v[152:155], 0
	s_waitcnt lgkmcnt(3)
	v_mfma_f32_16x16x32_bf16 v[28:31], v[128:131], v[160:163], 0
	v_mfma_f32_16x16x32_bf16 v[24:27], v[136:139], v[160:163], 0
	s_waitcnt lgkmcnt(1)
	v_mfma_f32_16x16x32_bf16 v[12:15], v[128:131], v[168:171], 0
	v_mfma_f32_16x16x32_bf16 v[8:11], v[136:139], v[168:171], 0
	v_mfma_f32_16x16x32_bf16 v[60:63], v[132:135], v[148:151], v[60:63]
	v_mfma_f32_16x16x32_bf16 v[56:59], v[140:143], v[148:151], v[56:59]
	v_mfma_f32_16x16x32_bf16 v[44:47], v[132:135], v[156:159], v[44:47]
	v_mfma_f32_16x16x32_bf16 v[40:43], v[140:143], v[156:159], v[40:43]
	v_mfma_f32_16x16x32_bf16 v[28:31], v[132:135], v[164:167], v[28:31]
	v_mfma_f32_16x16x32_bf16 v[24:27], v[140:143], v[164:167], v[24:27]
	s_waitcnt lgkmcnt(0)
	v_mfma_f32_16x16x32_bf16 v[12:15], v[132:135], v[172:175], v[12:15]
	v_mfma_f32_16x16x32_bf16 v[8:11], v[140:143], v[172:175], v[8:11]
	s_setprio 0
	s_barrier
	s_add_u32 s8, s24, s38
	s_addc_u32 s23, s18, s39
	s_and_b32 s9, s23, 0xffff
	s_mov_b32 m0, s70
	s_nop 0
	buffer_load_dwordx4 v223, s[8:11], 0 offen lds
	s_mov_b32 m0, s71
	s_nop 0
	buffer_load_dwordx4 v225, s[8:11], 0 offen lds
	s_waitcnt vmcnt(6)
	s_barrier
	s_setprio 1
	v_mfma_f32_16x16x32_bf16 v[52:55], v[176:179], v[144:147], 0
	v_mfma_f32_16x16x32_bf16 v[48:51], v[192:195], v[144:147], 0
	v_mfma_f32_16x16x32_bf16 v[36:39], v[176:179], v[152:155], 0
	v_mfma_f32_16x16x32_bf16 v[32:35], v[192:195], v[152:155], 0
	v_mfma_f32_16x16x32_bf16 v[20:23], v[176:179], v[160:163], 0
	v_mfma_f32_16x16x32_bf16 v[16:19], v[192:195], v[160:163], 0
	v_mfma_f32_16x16x32_bf16 v[4:7], v[176:179], v[168:171], 0
	v_mfma_f32_16x16x32_bf16 v[0:3], v[192:195], v[168:171], 0
	v_mfma_f32_16x16x32_bf16 v[52:55], v[180:183], v[148:151], v[52:55]
	v_mfma_f32_16x16x32_bf16 v[48:51], v[196:199], v[148:151], v[48:51]
	v_mfma_f32_16x16x32_bf16 v[36:39], v[180:183], v[156:159], v[36:39]
	v_mfma_f32_16x16x32_bf16 v[32:35], v[196:199], v[156:159], v[32:35]
	v_mfma_f32_16x16x32_bf16 v[20:23], v[180:183], v[164:167], v[20:23]
	v_mfma_f32_16x16x32_bf16 v[16:19], v[196:199], v[164:167], v[16:19]
	v_mfma_f32_16x16x32_bf16 v[4:7], v[180:183], v[172:175], v[4:7]
	v_mfma_f32_16x16x32_bf16 v[0:3], v[196:199], v[172:175], v[0:3]
	s_setprio 0
	s_barrier
	s_branch .Lkmid_772
	.p2align 6
	s_nop 0
	s_nop 0
	s_nop 0
	s_nop 0
	s_nop 0
	s_nop 0
	s_nop 0
	s_nop 0
	s_nop 0
	s_nop 0

;     __device__ __forceinline__ size_t a_off(const Unit& u) const { return (size_t)u.pm * atile; }
;     __device__ __forceinline__ size_t b_off(const Unit& u) const { return (size_t)u.pn * btile; }
;     __device__ __forceinline__ bool next(int i, Unit& u) const { const long L = (long)i * G + c; if (L >= NG * 8) return false; u.g = (int)(L >> 3); u.pm = (int)(L & 7); u.pn = 0; return true; }
;     __device__ __forceinline__ size_t a_off(const Unit& u) const { return ((size_t)u.g * NROW + (size_t)u.pm * BM) * KA * 2; }
;     __device__ __forceinline__ size_t b_off(const Unit& u) const { return (size_t)u.g * btile; }
;     __device__ __forceinline__ bool next(int i, Unit& u) const { if (i >= 2) return false; u.g = g; u.pm = 2 * b + i; u.pn = 0; return true; }
;     __device__ __forceinline__ size_t a_off(const Unit& u) const { return ((size_t)u.g * NROW + (size_t)u.pm * BM) * KA * 2; }
;     __device__ __forceinline__ size_t b_off(const Unit& u) const { return (size_t)u.g * btile; }
; #define PG8_LDA(dst, b, h) do { _Pragma("unroll") for (int m = 0; m < 4; ++m) _Pragma("unroll") for (int k = 0; k < 2; ++k) dst[m][k] = *(const LAS bf16x8*)(lds + PG8_SA(b, h) + aoff + m * 2048 + k * 1024); } while (0)
;     ...
;         const bool has_next = S.next(ui + 1, nxt);
;         const char* nA = has_next ? (const char*)Ap + S.a_off(nxt) : cA; const char* nB = has_next ? (const char*)Btp + S.b_off(nxt) : cB;
;         for (int t = 0; t < nt; t += 2) {
;             const bool last = (t == nt - 2);
;             const char* a1 = cA + (size_t)(t + 1) * kstep;
;             const char* a2 = last ? nA : cA + (size_t)(t + 2) * kstep; const char* b2 = last ? nB : cB + (size_t)(t + 2) * kstep;
;             const char* a3 = a2 + kstep; const char* b3 = b2 + kstep;
;             PG8_LDB(B0, 0, 0); PG8_SCHED; PG8_LDA(At, 0, 0); PG8_STAGE(PG8_SA(1, 1), a1 + hstepA, voffA);
;             PG8_WAIT_L(8); PG8_BAR; PG8_WAIT_L(0); PG8_MMA(0, 0, At, B0); PG8_BAR; PG8_SCHED;
;             PG8_LDB(B1, 0, 1); PG8_STAGE(PG8_SB(0, 0), b2, voffB);
;             PG8_BAR; PG8_WAIT_L(0); PG8_MMA(0, 1, At, B1); PG8_BAR;
;             PG8_LDA(At, 0, 1); PG8_STAGE(PG8_SA(0, 0), a2, voffA);
;             PG8_BAR; PG8_WAIT_L(0); PG8_MMA(1, 0, At, B0); PG8_BAR; PG8_SCHED;
;             PG8_STAGE(PG8_SB(0, 1), b2 + hstepB, voffB);
;             PG8_WAIT_V(6); PG8_BAR; PG8_MMA(1, 1, At, B1); PG8_BAR;
.Lnext_done_23079:
.LBB0_842:
	s_ashr_i32 s59, s58, 31
	s_lshl_b64 s[16:17], s[58:59], 19
	s_add_u32 s64, s20, s16
	s_addc_u32 s65, s21, s17
	s_ashr_i32 s53, s52, 31
	s_lshl_b64 s[16:17], s[52:53], 19
	s_add_u32 s66, s33, s16
	v_cmp_lt_i64_e64 s[12:13], s[12:13], v[118:119]
	s_addc_u32 s67, s35, s17
	s_andn2_b64 vcc, exec, s[68:69]
	s_cbranch_vccnz .Lkzero_844
	s_and_b64 s[16:17], s[12:13], exec
	s_cselect_b32 s22, s65, s27
	s_cselect_b32 s23, s64, s26
	s_cselect_b32 s53, s67, s25
	s_cselect_b32 s59, s66, s24
	s_add_u32 s94, s26, 0x100
	s_addc_u32 s95, s27, 0
	s_add_u32 s96, s24, 0x100
	s_addc_u32 s97, s25, 0
	s_mov_b32 s16, 0
	ds_read_b128 v[100:103], v141
	ds_read_b128 v[104:107], v141 offset:1024
	ds_read_b128 v[122:125], v141 offset:2048
	ds_read_b128 v[126:129], v141 offset:3072
	s_add_i32 vcc_lo, s16, 2
	s_cmp_eq_u32 s87, s16
	s_cselect_b32 s36, s23, s94
	s_cselect_b32 s26, s22, s95
	s_cselect_b32 s27, s53, s97
	s_cselect_b32 s28, s59, s96
	s_add_u32 s24, s36, 0x80
	s_addc_u32 s25, s26, 0
	s_add_u32 s16, s94, s0
	s_addc_u32 s17, s95, s1
	s_add_u32 s16, s16, 0xffffff80
	s_addc_u32 s17, s17, -1
	s_and_b32 s17, s17, 0xffff
	s_mov_b32 m0, s88
	ds_read_b128 v[130:133], v142
	ds_read_b128 v[150:153], v142 offset:1024
	ds_read_b128 v[154:157], v142 offset:2048
	ds_read_b128 v[158:161], v142 offset:3072
	ds_read_b128 v[162:165], v142 offset:4096
	ds_read_b128 v[166:169], v142 offset:5120
	ds_read_b128 v[170:173], v142 offset:6144
	ds_read_b128 v[174:177], v142 offset:7168
	buffer_load_dwordx4 v134, s[16:19], 0 offen lds
	s_mov_b32 m0, s89
	s_nop 0
	buffer_load_dwordx4 v136, s[16:19], 0 offen lds
	s_waitcnt lgkmcnt(8)
	s_barrier
	s_waitcnt lgkmcnt(0)
	s_setprio 1
	s_waitcnt lgkmcnt(7)
	v_mfma_f32_16x16x32_bf16 v[88:91], v[100:103], v[130:133], 0
	v_mfma_f32_16x16x32_bf16 v[96:99], v[122:125], v[130:133], 0
	s_waitcnt lgkmcnt(5)
	v_mfma_f32_16x16x32_bf16 v[76:79], v[100:103], v[154:157], 0
	v_mfma_f32_16x16x32_bf16 v[84:87], v[122:125], v[154:157], 0
	s_waitcnt lgkmcnt(3)
	v_mfma_f32_16x16x32_bf16 v[64:67], v[100:103], v[162:165], 0
	v_mfma_f32_16x16x32_bf16 v[72:75], v[122:125], v[162:165], 0
	s_waitcnt lgkmcnt(1)
	v_mfma_f32_16x16x32_bf16 v[52:55], v[100:103], v[170:173], 0
	v_mfma_f32_16x16x32_bf16 v[60:63], v[122:125], v[170:173], 0
	v_mfma_f32_16x16x32_bf16 v[88:91], v[104:107], v[150:153], v[88:91]
	v_mfma_f32_16x16x32_bf16 v[96:99], v[126:129], v[150:153], v[96:99]
	v_mfma_f32_16x16x32_bf16 v[76:79], v[104:107], v[158:161], v[76:79]
	v_mfma_f32_16x16x32_bf16 v[84:87], v[126:129], v[158:161], v[84:87]
	v_mfma_f32_16x16x32_bf16 v[64:67], v[104:107], v[166:169], v[64:67]
	v_mfma_f32_16x16x32_bf16 v[72:75], v[126:129], v[166:169], v[72:75]
	s_waitcnt lgkmcnt(0)
	v_mfma_f32_16x16x32_bf16 v[52:55], v[104:107], v[174:177], v[52:55]
	v_mfma_f32_16x16x32_bf16 v[60:63], v[126:129], v[174:177], v[60:63]
	s_setprio 0
	s_barrier
	s_and_b32 s29, s27, 0xffff
	s_mov_b32 s30, s18
	s_mov_b32 s31, s19
	s_mov_b32 m0, s73
	ds_read_b128 v[178:181], v143
	ds_read_b128 v[182:185], v143 offset:1024
	buffer_load_dwordx4 v135, s[28:31], 0 offen lds
	s_mov_b32 m0, s74
	s_nop 0
	buffer_load_dwordx4 v137, s[28:31], 0 offen lds
	s_barrier
	s_waitcnt lgkmcnt(0)
	s_setprio 1
	s_waitcnt lgkmcnt(1)
	v_mfma_f32_16x16x32_bf16 v[92:95], v[178:181], v[130:133], 0
	v_mfma_f32_16x16x32_bf16 v[80:83], v[178:181], v[154:157], 0
	v_mfma_f32_16x16x32_bf16 v[68:71], v[178:181], v[162:165], 0
	v_mfma_f32_16x16x32_bf16 v[56:59], v[178:181], v[170:173], 0
	s_waitcnt lgkmcnt(0)
	v_mfma_f32_16x16x32_bf16 v[92:95], v[182:185], v[150:153], v[92:95]
	v_mfma_f32_16x16x32_bf16 v[80:83], v[182:185], v[158:161], v[80:83]
	v_mfma_f32_16x16x32_bf16 v[68:71], v[182:185], v[166:169], v[68:71]
	v_mfma_f32_16x16x32_bf16 v[56:59], v[182:185], v[174:177], v[56:59]
	s_setprio 0
	s_and_b32 s37, s26, 0xffff
	s_mov_b32 s38, s18
	s_mov_b32 s39, s19
	s_mov_b32 m0, s71
	s_barrier
	ds_read_b128 v[130:133], v142 offset:16384
	ds_read_b128 v[150:153], v142 offset:17408
	ds_read_b128 v[154:157], v142 offset:18432
	ds_read_b128 v[158:161], v142 offset:19456
	ds_read_b128 v[162:165], v142 offset:20480
	ds_read_b128 v[166:169], v142 offset:21504
	ds_read_b128 v[170:173], v142 offset:22528
	ds_read_b128 v[174:177], v142 offset:23552
	buffer_load_dwordx4 v134, s[36:39], 0 offen lds
	s_mov_b32 m0, s75
	s_nop 0
	buffer_load_dwordx4 v136, s[36:39], 0 offen lds
	s_barrier
	s_waitcnt lgkmcnt(0)
	s_setprio 1
	s_waitcnt lgkmcnt(7)
	v_mfma_f32_16x16x32_bf16 v[44:47], v[100:103], v[130:133], 0
	v_mfma_f32_16x16x32_bf16 v[48:51], v[122:125], v[130:133], 0
	s_waitcnt lgkmcnt(5)
	v_mfma_f32_16x16x32_bf16 v[28:31], v[100:103], v[154:157], 0
	v_mfma_f32_16x16x32_bf16 v[36:39], v[122:125], v[154:157], 0
	s_waitcnt lgkmcnt(3)
	v_mfma_f32_16x16x32_bf16 v[12:15], v[100:103], v[162:165], 0
	v_mfma_f32_16x16x32_bf16 v[20:23], v[122:125], v[162:165], 0
	s_waitcnt lgkmcnt(1)
	v_mfma_f32_16x16x32_bf16 v[0:3], v[100:103], v[170:173], 0
	v_mfma_f32_16x16x32_bf16 v[8:11], v[122:125], v[170:173], 0
	v_mfma_f32_16x16x32_bf16 v[44:47], v[104:107], v[150:153], v[44:47]
	v_mfma_f32_16x16x32_bf16 v[48:51], v[126:129], v[150:153], v[48:51]
	v_mfma_f32_16x16x32_bf16 v[28:31], v[104:107], v[158:161], v[28:31]
	v_mfma_f32_16x16x32_bf16 v[36:39], v[126:129], v[158:161], v[36:39]
	v_mfma_f32_16x16x32_bf16 v[12:15], v[104:107], v[166:169], v[12:15]
	v_mfma_f32_16x16x32_bf16 v[20:23], v[126:129], v[166:169], v[20:23]
	s_waitcnt lgkmcnt(0)
	v_mfma_f32_16x16x32_bf16 v[0:3], v[104:107], v[174:177], v[0:3]
	v_mfma_f32_16x16x32_bf16 v[8:11], v[126:129], v[174:177], v[8:11]
	s_setprio 0
	s_barrier
	s_add_u32 s16, s28, s44
	s_addc_u32 vcc_hi, s27, s45
	s_and_b32 s17, vcc_hi, 0xffff
	s_mov_b32 m0, s76
	s_nop 0
	buffer_load_dwordx4 v135, s[16:19], 0 offen lds
	s_mov_b32 m0, s77
	s_nop 0
	buffer_load_dwordx4 v137, s[16:19], 0 offen lds
	s_waitcnt vmcnt(6)
	s_barrier
	s_setprio 1
	v_mfma_f32_16x16x32_bf16 v[40:43], v[178:181], v[130:133], 0
	v_mfma_f32_16x16x32_bf16 v[32:35], v[178:181], v[154:157], 0
	v_mfma_f32_16x16x32_bf16 v[16:19], v[178:181], v[162:165], 0
	v_mfma_f32_16x16x32_bf16 v[4:7], v[178:181], v[170:173], 0
	v_mfma_f32_16x16x32_bf16 v[40:43], v[182:185], v[150:153], v[40:43]
	v_mfma_f32_16x16x32_bf16 v[32:35], v[182:185], v[158:161], v[32:35]
	v_mfma_f32_16x16x32_bf16 v[16:19], v[182:185], v[166:169], v[16:19]
	v_mfma_f32_16x16x32_bf16 v[4:7], v[182:185], v[174:177], v[4:7]
	s_setprio 0
	s_barrier
	s_branch .Lkmid_844
	.p2align 6
	s_nop 0
	s_nop 0
	s_nop 0
	s_nop 0
	s_nop 0
	s_nop 0
	s_nop 0
	s_nop 0
	s_nop 0
	s_nop 0

;     __device__ __forceinline__ size_t a_off(const Unit& u) const { return (size_t)u.pm * atile; }
;     __device__ __forceinline__ size_t b_off(const Unit& u) const { return (size_t)u.pn * btile; }
;     __device__ __forceinline__ bool next(int i, Unit& u) const { const long L = (long)i * G + c; if (L >= NG * 8) return false; u.g = (int)(L >> 3); u.pm = (int)(L & 7); u.pn = 0; return true; }
;     __device__ __forceinline__ size_t a_off(const Unit& u) const { return ((size_t)u.g * NROW + (size_t)u.pm * BM) * KA * 2; }
;     __device__ __forceinline__ size_t b_off(const Unit& u) const { return (size_t)u.g * btile; }
;     __device__ __forceinline__ bool next(int i, Unit& u) const { if (i >= 2) return false; u.g = g; u.pm = 2 * b + i; u.pn = 0; return true; }
;     __device__ __forceinline__ size_t a_off(const Unit& u) const { return ((size_t)u.g * NROW + (size_t)u.pm * BM) * KA * 2; }
;     __device__ __forceinline__ size_t b_off(const Unit& u) const { return (size_t)u.g * btile; }
; #define PG8_STAGE(bufoff, gbase, voff) do { const __amdgpu_buffer_rsrc_t _r = __builtin_amdgcn_make_buffer_rsrc((void*)(gbase), (short)0, 0x7fffffff, 0x00020000); _Pragma("unroll") for (int _i = 0; _i < 2; ++_i) \
;         __builtin_amdgcn_raw_ptr_buffer_load_lds(_r, (LAS unsigned*)(lds + (bufoff) + ldsw + _i * 8192), 16, (int)(voff)[_i], 0, 0, 0); } while (0)
; #define PG8_WAIT_L(n) asm volatile("s_waitcnt lgkmcnt(" #n ")" ::: "memory")
; #define PG8_BAR __builtin_amdgcn_s_barrier()
; #define PG8_SCHED __builtin_amdgcn_sched_barrier(0)
;     ...
;         const bool has_next = S.next(ui + 1, nxt);
;         const char* nA = has_next ? (const char*)Ap + S.a_off(nxt) : cA; const char* nB = has_next ? (const char*)Btp + S.b_off(nxt) : cB;
;         for (int t = 0; t < nt; t += 2) {
;             const bool last = (t == nt - 2);
;             const char* a1 = cA + (size_t)(t + 1) * kstep;
;             const char* a2 = last ? nA : cA + (size_t)(t + 2) * kstep; const char* b2 = last ? nB : cB + (size_t)(t + 2) * kstep;
;             const char* a3 = a2 + kstep; const char* b3 = b2 + kstep;
;             PG8_LDB(B0, 0, 0); PG8_SCHED; PG8_LDA(At, 0, 0); PG8_STAGE(PG8_SA(1, 1), a1 + hstepA, voffA);
;             PG8_WAIT_L(8); PG8_BAR; PG8_WAIT_L(0); PG8_MMA(0, 0, At, B0); PG8_BAR; PG8_SCHED;
;             PG8_LDB(B1, 0, 1); PG8_STAGE(PG8_SB(0, 0), b2, voffB);
.LBB0_920:
	s_ashr_i32 s51, s50, 31
	s_lshl_b64 s[8:9], s[50:51], 19
	s_add_u32 s52, s40, s8
	s_addc_u32 s53, s41, s9
	s_ashr_i32 s49, s48, 31
	s_lshl_b64 s[8:9], s[48:49], 19
	s_add_u32 s58, s72, s8
	v_cmp_lt_i64_e64 s[0:1], s[0:1], v[188:189]
	s_addc_u32 s59, s73, s9
	s_andn2_b64 vcc, exec, s[46:47]
	s_waitcnt lgkmcnt(0)
	s_cbranch_vccnz .Lkzero_922
	s_and_b64 s[0:1], s[0:1], exec
	s_cselect_b32 s0, s53, s19
	s_cselect_b32 s1, s52, s18
	s_cselect_b32 s49, s59, s17
	s_cselect_b32 s51, s58, s16
	s_add_u32 s91, s18, 0x100
	s_addc_u32 s92, s19, 0
	s_add_u32 s93, s16, 0x100
	s_addc_u32 s94, s17, 0
	s_mov_b32 s8, 0
	ds_read_b128 v[128:131], v227
	ds_read_b128 v[132:135], v227 offset:1024
	ds_read_b128 v[136:139], v227 offset:2048
	ds_read_b128 v[140:143], v227 offset:3072
	s_add_i32 s22, s8, 2
	s_cmp_eq_u32 s87, s8
	s_cselect_b32 s28, s1, s91
	s_cselect_b32 s19, s0, s92
	s_cselect_b32 s18, s49, s94
	s_cselect_b32 s24, s51, s93
	s_add_u32 s16, s28, 0x80
	s_addc_u32 s17, s19, 0
	s_add_u32 s8, s91, s36
	s_addc_u32 s9, s92, s37
	s_add_u32 s8, s8, 0xffffff80
	s_addc_u32 s9, s9, -1
	s_and_b32 s9, s9, 0xffff
	s_mov_b32 m0, s88
	ds_read_b128 v[144:147], v228
	ds_read_b128 v[148:151], v228 offset:1024
	ds_read_b128 v[152:155], v228 offset:2048
	ds_read_b128 v[156:159], v228 offset:3072
	ds_read_b128 v[160:163], v228 offset:4096
	ds_read_b128 v[164:167], v228 offset:5120
	ds_read_b128 v[168:171], v228 offset:6144
	ds_read_b128 v[172:175], v228 offset:7168
	buffer_load_dwordx4 v222, s[8:11], 0 offen lds
	s_mov_b32 m0, s89
	s_nop 0
	buffer_load_dwordx4 v224, s[8:11], 0 offen lds
	s_waitcnt lgkmcnt(8)
	s_barrier
	s_waitcnt lgkmcnt(0)
	s_setprio 1
	s_waitcnt lgkmcnt(7)
	v_mfma_f32_16x16x32_bf16 v[120:123], v[128:131], v[144:147], 0
	v_mfma_f32_16x16x32_bf16 v[124:127], v[136:139], v[144:147], 0
	s_waitcnt lgkmcnt(5)
	v_mfma_f32_16x16x32_bf16 v[108:111], v[128:131], v[152:155], 0
	v_mfma_f32_16x16x32_bf16 v[104:107], v[136:139], v[152:155], 0
	s_waitcnt lgkmcnt(3)
	v_mfma_f32_16x16x32_bf16 v[92:95], v[128:131], v[160:163], 0
	v_mfma_f32_16x16x32_bf16 v[88:91], v[136:139], v[160:163], 0
	s_waitcnt lgkmcnt(1)
	v_mfma_f32_16x16x32_bf16 v[76:79], v[128:131], v[168:171], 0
	v_mfma_f32_16x16x32_bf16 v[72:75], v[136:139], v[168:171], 0
	v_mfma_f32_16x16x32_bf16 v[120:123], v[132:135], v[148:151], v[120:123]
	v_mfma_f32_16x16x32_bf16 v[124:127], v[140:143], v[148:151], v[124:127]
	v_mfma_f32_16x16x32_bf16 v[108:111], v[132:135], v[156:159], v[108:111]
	v_mfma_f32_16x16x32_bf16 v[104:107], v[140:143], v[156:159], v[104:107]
	v_mfma_f32_16x16x32_bf16 v[92:95], v[132:135], v[164:167], v[92:95]
	v_mfma_f32_16x16x32_bf16 v[88:91], v[140:143], v[164:167], v[88:91]
	s_waitcnt lgkmcnt(0)
	v_mfma_f32_16x16x32_bf16 v[76:79], v[132:135], v[172:175], v[76:79]
	v_mfma_f32_16x16x32_bf16 v[72:75], v[140:143], v[172:175], v[72:75]
	s_setprio 0
	s_barrier
	s_and_b32 s25, s18, 0xffff
	s_mov_b32 s26, s10
	s_mov_b32 s27, s11
	s_mov_b32 m0, s67
	ds_read_b128 v[176:179], v229
	ds_read_b128 v[180:183], v229 offset:1024
	ds_read_b128 v[192:195], v229 offset:2048
	ds_read_b128 v[196:199], v229 offset:3072
	buffer_load_dwordx4 v223, s[24:27], 0 offen lds
	s_mov_b32 m0, s74
	s_nop 0
	buffer_load_dwordx4 v225, s[24:27], 0 offen lds
	s_barrier
; #define PG8_STAGE(bufoff, gbase, voff) do { const __amdgpu_buffer_rsrc_t _r = __builtin_amdgcn_make_buffer_rsrc((void*)(gbase), (short)0, 0x7fffffff, 0x00020000); _Pragma("unroll") for (int _i = 0; _i < 2; ++_i) \
;         __builtin_amdgcn_raw_ptr_buffer_load_lds(_r, (LAS unsigned*)(lds + (bufoff) + ldsw + _i * 8192), 16, (int)(voff)[_i], 0, 0, 0); } while (0)
; #define PG8_LDA(dst, b, h) do { _Pragma("unroll") for (int m = 0; m < 4; ++m) _Pragma("unroll") for (int k = 0; k < 2; ++k) dst[m][k] = *(const LAS bf16x8*)(lds + PG8_SA(b, h) + aoff + m * 2048 + k * 1024); } while (0)
; #define PG8_MMA(ai, bj, At, Bt) do { __builtin_amdgcn_s_setprio(1); _Pragma("unroll") for (int k = 0; k < 2; ++k) _Pragma("unroll") for (int m = 0; m < 4; ++m) _Pragma("unroll") for (int n = 0; n < ((bj) == 1 ? NB1 : 2); ++n) \
;         acc[ai][bj][m][n] = __builtin_amdgcn_mfma_f32_16x16x32_bf16(Bt[n][k], At[m][k], acc[ai][bj][m][n], 0, 0, 0); __builtin_amdgcn_s_setprio(0); } while (0)
; #define PG8_WAIT_V(n) asm volatile("s_waitcnt vmcnt(" #n ")" ::: "memory")
; #define PG8_WAIT_L(n) asm volatile("s_waitcnt lgkmcnt(" #n ")" ::: "memory")
; #define PG8_BAR __builtin_amdgcn_s_barrier()
; #define PG8_SCHED __builtin_amdgcn_sched_barrier(0)
;     ...
;             PG8_BAR; PG8_WAIT_L(0); PG8_MMA(0, 1, At, B1); PG8_BAR;
;             PG8_LDA(At, 0, 1); PG8_STAGE(PG8_SA(0, 0), a2, voffA);
;             PG8_BAR; PG8_WAIT_L(0); PG8_MMA(1, 0, At, B0); PG8_BAR; PG8_SCHED;
;             PG8_STAGE(PG8_SB(0, 1), b2 + hstepB, voffB);
;             PG8_WAIT_V(6); PG8_BAR; PG8_MMA(1, 1, At, B1); PG8_BAR;
	s_waitcnt lgkmcnt(0)
	s_setprio 1
	s_waitcnt lgkmcnt(3)
	v_mfma_f32_16x16x32_bf16 v[116:119], v[176:179], v[144:147], 0
	s_waitcnt lgkmcnt(1)
	v_mfma_f32_16x16x32_bf16 v[112:115], v[192:195], v[144:147], 0
	v_mfma_f32_16x16x32_bf16 v[100:103], v[176:179], v[152:155], 0
	v_mfma_f32_16x16x32_bf16 v[96:99], v[192:195], v[152:155], 0
	v_mfma_f32_16x16x32_bf16 v[84:87], v[176:179], v[160:163], 0
	v_mfma_f32_16x16x32_bf16 v[80:83], v[192:195], v[160:163], 0
	v_mfma_f32_16x16x32_bf16 v[68:71], v[176:179], v[168:171], 0
	v_mfma_f32_16x16x32_bf16 v[64:67], v[192:195], v[168:171], 0
	v_mfma_f32_16x16x32_bf16 v[116:119], v[180:183], v[148:151], v[116:119]
	s_waitcnt lgkmcnt(0)
	v_mfma_f32_16x16x32_bf16 v[112:115], v[196:199], v[148:151], v[112:115]
	v_mfma_f32_16x16x32_bf16 v[100:103], v[180:183], v[156:159], v[100:103]
	v_mfma_f32_16x16x32_bf16 v[96:99], v[196:199], v[156:159], v[96:99]
	v_mfma_f32_16x16x32_bf16 v[84:87], v[180:183], v[164:167], v[84:87]
	v_mfma_f32_16x16x32_bf16 v[80:83], v[196:199], v[164:167], v[80:83]
	v_mfma_f32_16x16x32_bf16 v[68:71], v[180:183], v[172:175], v[68:71]
	v_mfma_f32_16x16x32_bf16 v[64:67], v[196:199], v[172:175], v[64:67]
	s_setprio 0
	s_and_b32 s29, s19, 0xffff
	s_mov_b32 s30, s10
	s_mov_b32 s31, s11
	s_mov_b32 m0, s65
	s_barrier
	ds_read_b128 v[144:147], v228 offset:16384
	ds_read_b128 v[148:151], v228 offset:17408
	ds_read_b128 v[152:155], v228 offset:18432
	ds_read_b128 v[156:159], v228 offset:19456
	ds_read_b128 v[160:163], v228 offset:20480
	ds_read_b128 v[164:167], v228 offset:21504
	ds_read_b128 v[168:171], v228 offset:22528
	ds_read_b128 v[172:175], v228 offset:23552
	buffer_load_dwordx4 v222, s[28:31], 0 offen lds
	s_mov_b32 m0, s75
	s_nop 0
	buffer_load_dwordx4 v224, s[28:31], 0 offen lds
	s_barrier
	s_waitcnt lgkmcnt(0)
	s_setprio 1
	s_waitcnt lgkmcnt(7)
	v_mfma_f32_16x16x32_bf16 v[60:63], v[128:131], v[144:147], 0
	v_mfma_f32_16x16x32_bf16 v[56:59], v[136:139], v[144:147], 0
	s_waitcnt lgkmcnt(5)
	v_mfma_f32_16x16x32_bf16 v[44:47], v[128:131], v[152:155], 0
	v_mfma_f32_16x16x32_bf16 v[40:43], v[136:139], v[152:155], 0
	s_waitcnt lgkmcnt(3)
	v_mfma_f32_16x16x32_bf16 v[28:31], v[128:131], v[160:163], 0
	v_mfma_f32_16x16x32_bf16 v[24:27], v[136:139], v[160:163], 0
	s_waitcnt lgkmcnt(1)
	v_mfma_f32_16x16x32_bf16 v[12:15], v[128:131], v[168:171], 0
	v_mfma_f32_16x16x32_bf16 v[8:11], v[136:139], v[168:171], 0
	v_mfma_f32_16x16x32_bf16 v[60:63], v[132:135], v[148:151], v[60:63]
	v_mfma_f32_16x16x32_bf16 v[56:59], v[140:143], v[148:151], v[56:59]
	v_mfma_f32_16x16x32_bf16 v[44:47], v[132:135], v[156:159], v[44:47]
	v_mfma_f32_16x16x32_bf16 v[40:43], v[140:143], v[156:159], v[40:43]
	v_mfma_f32_16x16x32_bf16 v[28:31], v[132:135], v[164:167], v[28:31]
	v_mfma_f32_16x16x32_bf16 v[24:27], v[140:143], v[164:167], v[24:27]
	s_waitcnt lgkmcnt(0)
	v_mfma_f32_16x16x32_bf16 v[12:15], v[132:135], v[172:175], v[12:15]
	v_mfma_f32_16x16x32_bf16 v[8:11], v[140:143], v[172:175], v[8:11]
	s_setprio 0
	s_barrier
	s_add_u32 s8, s24, s38
	s_addc_u32 s23, s18, s39
	s_and_b32 s9, s23, 0xffff
	s_mov_b32 m0, s76
	s_nop 0
	buffer_load_dwordx4 v223, s[8:11], 0 offen lds
	s_mov_b32 m0, s77
	s_nop 0
	buffer_load_dwordx4 v225, s[8:11], 0 offen lds
	s_waitcnt vmcnt(6)
	s_barrier
	s_setprio 1
	v_mfma_f32_16x16x32_bf16 v[52:55], v[176:179], v[144:147], 0
	v_mfma_f32_16x16x32_bf16 v[48:51], v[192:195], v[144:147], 0
	v_mfma_f32_16x16x32_bf16 v[36:39], v[176:179], v[152:155], 0
	v_mfma_f32_16x16x32_bf16 v[32:35], v[192:195], v[152:155], 0
	v_mfma_f32_16x16x32_bf16 v[20:23], v[176:179], v[160:163], 0
	v_mfma_f32_16x16x32_bf16 v[16:19], v[192:195], v[160:163], 0
	v_mfma_f32_16x16x32_bf16 v[4:7], v[176:179], v[168:171], 0
	v_mfma_f32_16x16x32_bf16 v[0:3], v[192:195], v[168:171], 0
	v_mfma_f32_16x16x32_bf16 v[52:55], v[180:183], v[148:151], v[52:55]
	v_mfma_f32_16x16x32_bf16 v[48:51], v[196:199], v[148:151], v[48:51]
	v_mfma_f32_16x16x32_bf16 v[36:39], v[180:183], v[156:159], v[36:39]
	v_mfma_f32_16x16x32_bf16 v[32:35], v[196:199], v[156:159], v[32:35]
	v_mfma_f32_16x16x32_bf16 v[20:23], v[180:183], v[164:167], v[20:23]
	v_mfma_f32_16x16x32_bf16 v[16:19], v[196:199], v[164:167], v[16:19]
	v_mfma_f32_16x16x32_bf16 v[4:7], v[180:183], v[172:175], v[4:7]
	v_mfma_f32_16x16x32_bf16 v[0:3], v[196:199], v[172:175], v[0:3]
	s_setprio 0
	s_barrier
	s_branch .Lkmid_922
	.p2align 6
	s_nop 0
	s_nop 0
	s_nop 0
	s_nop 0
	s_nop 0
	s_nop 0
	s_nop 0
	s_nop 0
	s_nop 0
	s_nop 0

;     __device__ __forceinline__ size_t a_off(const Unit& u) const { return (size_t)u.pm * atile; }
;     __device__ __forceinline__ size_t b_off(const Unit& u) const { return (size_t)u.pn * btile; }
;     __device__ __forceinline__ bool next(int i, Unit& u) const { const long L = (long)i * G + c; if (L >= NG * 8) return false; u.g = (int)(L >> 3); u.pm = (int)(L & 7); u.pn = 0; return true; }
;     __device__ __forceinline__ size_t a_off(const Unit& u) const { return ((size_t)u.g * NROW + (size_t)u.pm * BM) * KA * 2; }
;     __device__ __forceinline__ size_t b_off(const Unit& u) const { return (size_t)u.g * btile; }
;     __device__ __forceinline__ bool next(int i, Unit& u) const { if (i >= 2) return false; u.g = g; u.pm = 2 * b + i; u.pn = 0; return true; }
;     __device__ __forceinline__ size_t a_off(const Unit& u) const { return ((size_t)u.g * NROW + (size_t)u.pm * BM) * KA * 2; }
;     __device__ __forceinline__ size_t b_off(const Unit& u) const { return (size_t)u.g * btile; }
; #define PG8_STAGE(bufoff, gbase, voff) do { const __amdgpu_buffer_rsrc_t _r = __builtin_amdgcn_make_buffer_rsrc((void*)(gbase), (short)0, 0x7fffffff, 0x00020000); _Pragma("unroll") for (int _i = 0; _i < 2; ++_i) \
;         __builtin_amdgcn_raw_ptr_buffer_load_lds(_r, (LAS unsigned*)(lds + (bufoff) + ldsw + _i * 8192), 16, (int)(voff)[_i], 0, 0, 0); } while (0)
; #define PG8_WAIT_L(n) asm volatile("s_waitcnt lgkmcnt(" #n ")" ::: "memory")
; #define PG8_BAR __builtin_amdgcn_s_barrier()
; #define PG8_SCHED __builtin_amdgcn_sched_barrier(0)
;     ...
;         const bool has_next = S.next(ui + 1, nxt);
;         const char* nA = has_next ? (const char*)Ap + S.a_off(nxt) : cA; const char* nB = has_next ? (const char*)Btp + S.b_off(nxt) : cB;
;         for (int t = 0; t < nt; t += 2) {
;             const bool last = (t == nt - 2);
;             const char* a1 = cA + (size_t)(t + 1) * kstep;
;             const char* a2 = last ? nA : cA + (size_t)(t + 2) * kstep; const char* b2 = last ? nB : cB + (size_t)(t + 2) * kstep;
;             const char* a3 = a2 + kstep; const char* b3 = b2 + kstep;
;             PG8_LDB(B0, 0, 0); PG8_SCHED; PG8_LDA(At, 0, 0); PG8_STAGE(PG8_SA(1, 1), a1 + hstepA, voffA);
;             PG8_WAIT_L(8); PG8_BAR; PG8_WAIT_L(0); PG8_MMA(0, 0, At, B0); PG8_BAR; PG8_SCHED;
;             PG8_LDB(B1, 0, 1); PG8_STAGE(PG8_SB(0, 0), b2, voffB);
.Lnext_done_28037:
.LBB0_982:
	s_ashr_i32 s57, s56, 31
	s_lshl_b64 s[16:17], s[56:57], 19
	s_add_u32 s58, s20, s16
	s_addc_u32 s59, s21, s17
	s_ashr_i32 s53, s52, 31
	s_lshl_b64 s[16:17], s[52:53], 19
	s_add_u32 s64, s75, s16
	v_cmp_lt_i64_e64 s[12:13], s[12:13], v[170:171]
	s_addc_u32 s65, s76, s17
	s_andn2_b64 vcc, exec, s[50:51]
	s_cbranch_vccnz .Lkzero_984
	s_and_b64 s[16:17], s[12:13], exec
	s_cselect_b32 s53, s59, s27
	s_cselect_b32 s57, s58, s26
	s_cselect_b32 s94, s65, s25
	s_cselect_b32 s95, s64, s24
	s_add_u32 s96, s26, 0x100
	s_addc_u32 s97, s27, 0
	s_add_u32 vcc_lo, s24, 0x100
	s_addc_u32 vcc_hi, s25, 0
	s_mov_b32 s16, 0
	ds_read_b128 v[76:79], v193
	ds_read_b128 v[88:91], v193 offset:1024
	ds_read_b128 v[92:95], v193 offset:2048
	ds_read_b128 v[128:131], v193 offset:3072
	s_add_i32 s22, s16, 2
	s_cmp_eq_u32 s90, s16
	s_cselect_b32 s36, s57, s96
	s_cselect_b32 s26, s53, s97
	s_cselect_b32 s25, s94, vcc_hi
	s_cselect_b32 s28, s95, vcc_lo
	s_add_u32 s24, s36, 0x80
	s_addc_u32 s23, s26, 0
	s_add_u32 s16, s96, s44
	s_addc_u32 s17, s97, s45
	s_add_u32 s16, s16, 0xffffff80
	s_addc_u32 s17, s17, -1
	s_and_b32 s17, s17, 0xffff
	s_mov_b32 m0, s91
	ds_read_b128 v[132:135], v194
	ds_read_b128 v[136:139], v194 offset:1024
	ds_read_b128 v[140:143], v194 offset:2048
	ds_read_b128 v[174:177], v194 offset:3072
	ds_read_b128 v[178:181], v194 offset:4096
	ds_read_b128 v[182:185], v194 offset:5120
	ds_read_b128 v[202:205], v194 offset:6144
	ds_read_b128 v[206:209], v194 offset:7168
	buffer_load_dwordx4 v186, s[16:19], 0 offen lds
	s_mov_b32 m0, s92
	s_nop 0
	buffer_load_dwordx4 v188, s[16:19], 0 offen lds
	s_waitcnt lgkmcnt(8)
	s_barrier
	s_waitcnt lgkmcnt(0)
	s_setprio 1
	s_waitcnt lgkmcnt(7)
	v_mfma_f32_16x16x32_bf16 v[152:155], v[76:79], v[132:135], 0
	v_mfma_f32_16x16x32_bf16 v[144:147], v[92:95], v[132:135], 0
	s_waitcnt lgkmcnt(5)
	v_mfma_f32_16x16x32_bf16 v[124:127], v[76:79], v[140:143], 0
	v_mfma_f32_16x16x32_bf16 v[120:123], v[92:95], v[140:143], 0
	s_waitcnt lgkmcnt(3)
	v_mfma_f32_16x16x32_bf16 v[108:111], v[76:79], v[178:181], 0
	v_mfma_f32_16x16x32_bf16 v[104:107], v[92:95], v[178:181], 0
	s_waitcnt lgkmcnt(1)
	v_mfma_f32_16x16x32_bf16 v[84:87], v[76:79], v[202:205], 0
	v_mfma_f32_16x16x32_bf16 v[80:83], v[92:95], v[202:205], 0
	v_mfma_f32_16x16x32_bf16 v[152:155], v[88:91], v[136:139], v[152:155]
	v_mfma_f32_16x16x32_bf16 v[144:147], v[128:131], v[136:139], v[144:147]
	v_mfma_f32_16x16x32_bf16 v[124:127], v[88:91], v[174:177], v[124:127]
	v_mfma_f32_16x16x32_bf16 v[120:123], v[128:131], v[174:177], v[120:123]
	v_mfma_f32_16x16x32_bf16 v[108:111], v[88:91], v[182:185], v[108:111]
	v_mfma_f32_16x16x32_bf16 v[104:107], v[128:131], v[182:185], v[104:107]
	s_waitcnt lgkmcnt(0)
	v_mfma_f32_16x16x32_bf16 v[84:87], v[88:91], v[206:209], v[84:87]
	v_mfma_f32_16x16x32_bf16 v[80:83], v[128:131], v[206:209], v[80:83]
	s_setprio 0
	s_barrier
	s_and_b32 s29, s25, 0xffff
	s_mov_b32 s30, s18
	s_mov_b32 s31, s19
	s_mov_b32 m0, s71
	ds_read_b128 v[210:213], v195
	ds_read_b128 v[214:217], v195 offset:1024
	ds_read_b128 v[218:221], v195 offset:2048
	ds_read_b128 v[222:225], v195 offset:3072
	buffer_load_dwordx4 v187, s[28:31], 0 offen lds
	s_mov_b32 m0, s77
	s_nop 0
	buffer_load_dwordx4 v189, s[28:31], 0 offen lds
	s_barrier
; #define PG8_STAGE(bufoff, gbase, voff) do { const __amdgpu_buffer_rsrc_t _r = __builtin_amdgcn_make_buffer_rsrc((void*)(gbase), (short)0, 0x7fffffff, 0x00020000); _Pragma("unroll") for (int _i = 0; _i < 2; ++_i) \
;         __builtin_amdgcn_raw_ptr_buffer_load_lds(_r, (LAS unsigned*)(lds + (bufoff) + ldsw + _i * 8192), 16, (int)(voff)[_i], 0, 0, 0); } while (0)
; #define PG8_LDA(dst, b, h) do { _Pragma("unroll") for (int m = 0; m < 4; ++m) _Pragma("unroll") for (int k = 0; k < 2; ++k) dst[m][k] = *(const LAS bf16x8*)(lds + PG8_SA(b, h) + aoff + m * 2048 + k * 1024); } while (0)
; #define PG8_MMA(ai, bj, At, Bt) do { __builtin_amdgcn_s_setprio(1); _Pragma("unroll") for (int k = 0; k < 2; ++k) _Pragma("unroll") for (int m = 0; m < 4; ++m) _Pragma("unroll") for (int n = 0; n < ((bj) == 1 ? NB1 : 2); ++n) \
;         acc[ai][bj][m][n] = __builtin_amdgcn_mfma_f32_16x16x32_bf16(Bt[n][k], At[m][k], acc[ai][bj][m][n], 0, 0, 0); __builtin_amdgcn_s_setprio(0); } while (0)
; #define PG8_WAIT_V(n) asm volatile("s_waitcnt vmcnt(" #n ")" ::: "memory")
; #define PG8_WAIT_L(n) asm volatile("s_waitcnt lgkmcnt(" #n ")" ::: "memory")
; #define PG8_BAR __builtin_amdgcn_s_barrier()
; #define PG8_SCHED __builtin_amdgcn_sched_barrier(0)
;     ...
;             PG8_BAR; PG8_WAIT_L(0); PG8_MMA(0, 1, At, B1); PG8_BAR;
;             PG8_LDA(At, 0, 1); PG8_STAGE(PG8_SA(0, 0), a2, voffA);
;             PG8_BAR; PG8_WAIT_L(0); PG8_MMA(1, 0, At, B0); PG8_BAR; PG8_SCHED;
;             PG8_STAGE(PG8_SB(0, 1), b2 + hstepB, voffB);
;             PG8_WAIT_V(6); PG8_BAR; PG8_MMA(1, 1, At, B1); PG8_BAR;
	s_waitcnt lgkmcnt(0)
	s_setprio 1
	s_waitcnt lgkmcnt(3)
	v_mfma_f32_16x16x32_bf16 v[116:119], v[210:213], v[140:143], 0
	s_waitcnt lgkmcnt(1)
	v_mfma_f32_16x16x32_bf16 v[112:115], v[218:221], v[140:143], 0
	v_mfma_f32_16x16x32_bf16 v[100:103], v[210:213], v[178:181], 0
	v_mfma_f32_16x16x32_bf16 v[96:99], v[218:221], v[178:181], 0
	v_mfma_f32_16x16x32_bf16 v[68:71], v[210:213], v[202:205], 0
	v_mfma_f32_16x16x32_bf16 v[64:67], v[218:221], v[202:205], 0
	v_mfma_f32_16x16x32_bf16 v[156:159], v[210:213], v[132:135], 0
	v_mfma_f32_16x16x32_bf16 v[132:135], v[218:221], v[132:135], 0
	v_mfma_f32_16x16x32_bf16 v[116:119], v[214:217], v[174:177], v[116:119]
	s_waitcnt lgkmcnt(0)
	v_mfma_f32_16x16x32_bf16 v[112:115], v[222:225], v[174:177], v[112:115]
	v_mfma_f32_16x16x32_bf16 v[100:103], v[214:217], v[182:185], v[100:103]
	v_mfma_f32_16x16x32_bf16 v[96:99], v[222:225], v[182:185], v[96:99]
	v_mfma_f32_16x16x32_bf16 v[68:71], v[214:217], v[206:209], v[68:71]
	v_mfma_f32_16x16x32_bf16 v[64:67], v[222:225], v[206:209], v[64:67]
	v_mfma_f32_16x16x32_bf16 v[140:143], v[214:217], v[136:139], v[156:159]
	v_mfma_f32_16x16x32_bf16 v[132:135], v[222:225], v[136:139], v[132:135]
	s_setprio 0
	s_and_b32 s37, s26, 0xffff
	s_mov_b32 s38, s18
	s_mov_b32 s39, s19
	s_mov_b32 m0, s67
	s_barrier
	ds_read_b128 v[136:139], v194 offset:16384
	ds_read_b128 v[148:151], v194 offset:17408
	ds_read_b128 v[156:159], v194 offset:18432
	ds_read_b128 v[174:177], v194 offset:19456
	ds_read_b128 v[178:181], v194 offset:20480
	ds_read_b128 v[182:185], v194 offset:21504
	ds_read_b128 v[202:205], v194 offset:22528
	ds_read_b128 v[206:209], v194 offset:23552
	buffer_load_dwordx4 v186, s[36:39], 0 offen lds
	s_mov_b32 m0, s78
	s_nop 0
	buffer_load_dwordx4 v188, s[36:39], 0 offen lds
	s_barrier
	s_waitcnt lgkmcnt(0)
	s_setprio 1
	s_waitcnt lgkmcnt(7)
	v_mfma_f32_16x16x32_bf16 v[60:63], v[76:79], v[136:139], 0
	v_mfma_f32_16x16x32_bf16 v[52:55], v[92:95], v[136:139], 0
	s_waitcnt lgkmcnt(5)
	v_mfma_f32_16x16x32_bf16 v[44:47], v[76:79], v[156:159], 0
	v_mfma_f32_16x16x32_bf16 v[40:43], v[92:95], v[156:159], 0
	s_waitcnt lgkmcnt(3)
	v_mfma_f32_16x16x32_bf16 v[28:31], v[76:79], v[178:181], 0
	v_mfma_f32_16x16x32_bf16 v[24:27], v[92:95], v[178:181], 0
	s_waitcnt lgkmcnt(1)
	v_mfma_f32_16x16x32_bf16 v[12:15], v[76:79], v[202:205], 0
	v_mfma_f32_16x16x32_bf16 v[8:11], v[92:95], v[202:205], 0
	v_mfma_f32_16x16x32_bf16 v[60:63], v[88:91], v[148:151], v[60:63]
	v_mfma_f32_16x16x32_bf16 v[52:55], v[128:131], v[148:151], v[52:55]
	v_mfma_f32_16x16x32_bf16 v[44:47], v[88:91], v[174:177], v[44:47]
	v_mfma_f32_16x16x32_bf16 v[40:43], v[128:131], v[174:177], v[40:43]
	v_mfma_f32_16x16x32_bf16 v[28:31], v[88:91], v[182:185], v[28:31]
	v_mfma_f32_16x16x32_bf16 v[24:27], v[128:131], v[182:185], v[24:27]
	s_waitcnt lgkmcnt(0)
	v_mfma_f32_16x16x32_bf16 v[12:15], v[88:91], v[206:209], v[12:15]
	v_mfma_f32_16x16x32_bf16 v[8:11], v[128:131], v[206:209], v[8:11]
	s_setprio 0
	s_barrier
	s_add_u32 s16, s28, s46
	s_addc_u32 s14, s25, s47
	s_and_b32 s17, s14, 0xffff
	s_mov_b32 m0, s79
	s_nop 0
	buffer_load_dwordx4 v187, s[16:19], 0 offen lds
	s_mov_b32 m0, s80
	s_nop 0
	buffer_load_dwordx4 v189, s[16:19], 0 offen lds
	s_waitcnt vmcnt(6)
	s_barrier
	s_setprio 1
	v_mfma_f32_16x16x32_bf16 v[56:59], v[210:213], v[136:139], 0
	v_mfma_f32_16x16x32_bf16 v[48:51], v[218:221], v[136:139], 0
	v_mfma_f32_16x16x32_bf16 v[36:39], v[210:213], v[156:159], 0
	v_mfma_f32_16x16x32_bf16 v[32:35], v[218:221], v[156:159], 0
	v_mfma_f32_16x16x32_bf16 v[20:23], v[210:213], v[178:181], 0
	v_mfma_f32_16x16x32_bf16 v[16:19], v[218:221], v[178:181], 0
	v_mfma_f32_16x16x32_bf16 v[4:7], v[210:213], v[202:205], 0
	v_mfma_f32_16x16x32_bf16 v[0:3], v[218:221], v[202:205], 0
	v_mfma_f32_16x16x32_bf16 v[56:59], v[214:217], v[148:151], v[56:59]
	v_mfma_f32_16x16x32_bf16 v[48:51], v[222:225], v[148:151], v[48:51]
	v_mfma_f32_16x16x32_bf16 v[36:39], v[214:217], v[174:177], v[36:39]
	v_mfma_f32_16x16x32_bf16 v[32:35], v[222:225], v[174:177], v[32:35]
	v_mfma_f32_16x16x32_bf16 v[20:23], v[214:217], v[182:185], v[20:23]
	v_mfma_f32_16x16x32_bf16 v[16:19], v[222:225], v[182:185], v[16:19]
	v_mfma_f32_16x16x32_bf16 v[4:7], v[214:217], v[206:209], v[4:7]
	v_mfma_f32_16x16x32_bf16 v[0:3], v[222:225], v[206:209], v[0:3]
	s_setprio 0
	s_barrier
	s_branch .Lkmid_984
	.p2align 6
	s_nop 0
	s_nop 0
	s_nop 0
	s_nop 0
	s_nop 0
	s_nop 0
	s_nop 0
	s_nop 0
	s_nop 0
	s_nop 0

; #define PG8_STAGE(bufoff, gbase, voff) do { const __amdgpu_buffer_rsrc_t _r = __builtin_amdgcn_make_buffer_rsrc((void*)(gbase), (short)0, 0x7fffffff, 0x00020000); _Pragma("unroll") for (int _i = 0; _i < 2; ++_i) \
;         __builtin_amdgcn_raw_ptr_buffer_load_lds(_r, (LAS unsigned*)(lds + (bufoff) + ldsw + _i * 8192), 16, (int)(voff)[_i], 0, 0, 0); } while (0)
; #define PG8_LDA(dst, b, h) do { _Pragma("unroll") for (int m = 0; m < 4; ++m) _Pragma("unroll") for (int k = 0; k < 2; ++k) dst[m][k] = *(const LAS bf16x8*)(lds + PG8_SA(b, h) + aoff + m * 2048 + k * 1024); } while (0)
; #define PG8_LDB(dst, b, h) do { _Pragma("unroll") for (int n = 0; n < 2; ++n) _Pragma("unroll") for (int k = 0; k < 2; ++k) dst[n][k] = *(const LAS bf16x8*)(lds + PG8_SB(b, h) + boff + n * 2048 + k * 1024); } while (0)
; #define PG8_MMA(ai, bj, At, Bt) do { __builtin_amdgcn_s_setprio(1); _Pragma("unroll") for (int k = 0; k < 2; ++k) _Pragma("unroll") for (int m = 0; m < 4; ++m) _Pragma("unroll") for (int n = 0; n < ((bj) == 1 ? NB1 : 2); ++n) \
;         acc[ai][bj][m][n] = __builtin_amdgcn_mfma_f32_16x16x32_bf16(Bt[n][k], At[m][k], acc[ai][bj][m][n], 0, 0, 0); __builtin_amdgcn_s_setprio(0); } while (0)
; #define PG8_WAIT_L(n) asm volatile("s_waitcnt lgkmcnt(" #n ")" ::: "memory")
; #define PG8_BAR __builtin_amdgcn_s_barrier()
; #define PG8_SCHED __builtin_amdgcn_sched_barrier(0)
;     ...
;             const bool last = (t == nt - 2);
;             const char* a1 = cA + (size_t)(t + 1) * kstep;
;             const char* a2 = last ? nA : cA + (size_t)(t + 2) * kstep; const char* b2 = last ? nB : cB + (size_t)(t + 2) * kstep;
;             const char* a3 = a2 + kstep; const char* b3 = b2 + kstep;
;             PG8_LDB(B0, 0, 0); PG8_SCHED; PG8_LDA(At, 0, 0); PG8_STAGE(PG8_SA(1, 1), a1 + hstepA, voffA);
;             PG8_WAIT_L(8); PG8_BAR; PG8_WAIT_L(0); PG8_MMA(0, 0, At, B0); PG8_BAR; PG8_SCHED;
;             PG8_LDB(B1, 0, 1); PG8_STAGE(PG8_SB(0, 0), b2, voffB);
;             PG8_BAR; PG8_WAIT_L(0); PG8_MMA(0, 1, At, B1); PG8_BAR;
.LBB0_1064:
	s_andn2_b64 vcc, exec, s[42:43]
	s_waitcnt lgkmcnt(0)
	s_cbranch_vccnz .Lkzero_1066
	s_add_u32 s79, s18, 0x100
	s_addc_u32 s80, s19, 0
	s_add_u32 s81, s16, 0x100
	s_addc_u32 s82, s17, 0
	s_mov_b32 s8, 0
	ds_read_b128 v[128:131], v227
	ds_read_b128 v[132:135], v227 offset:1024
	ds_read_b128 v[136:139], v227 offset:2048
	ds_read_b128 v[140:143], v227 offset:3072
	s_add_i32 s22, s8, 2
	s_cmp_eq_u32 s71, s8
	s_cselect_b32 s28, s0, s79
	s_cselect_b32 s19, s1, s80
	s_cselect_b32 s18, s45, s82
	s_cselect_b32 s24, s44, s81
	s_add_u32 s16, s28, 0x80
	s_addc_u32 s17, s19, 0
	s_add_u32 s8, s79, s36
	s_addc_u32 s9, s80, s37
	s_add_u32 s8, s8, 0xffffff80
	s_addc_u32 s9, s9, -1
	s_and_b32 s9, s9, 0xffff
	s_mov_b32 m0, s72
	ds_read_b128 v[144:147], v228
	ds_read_b128 v[148:151], v228 offset:1024
	ds_read_b128 v[152:155], v228 offset:2048
	ds_read_b128 v[156:159], v228 offset:3072
	ds_read_b128 v[160:163], v228 offset:4096
	ds_read_b128 v[164:167], v228 offset:5120
	ds_read_b128 v[168:171], v228 offset:6144
	ds_read_b128 v[172:175], v228 offset:7168
	buffer_load_dwordx4 v222, s[8:11], 0 offen lds
	s_mov_b32 m0, s73
	s_nop 0
	buffer_load_dwordx4 v224, s[8:11], 0 offen lds
	s_waitcnt lgkmcnt(8)
	s_barrier
	s_waitcnt lgkmcnt(0)
	s_setprio 1
	s_waitcnt lgkmcnt(7)
	v_mfma_f32_16x16x32_bf16 v[120:123], v[128:131], v[144:147], 0
	v_mfma_f32_16x16x32_bf16 v[124:127], v[136:139], v[144:147], 0
	s_waitcnt lgkmcnt(5)
	v_mfma_f32_16x16x32_bf16 v[108:111], v[128:131], v[152:155], 0
	v_mfma_f32_16x16x32_bf16 v[104:107], v[136:139], v[152:155], 0
	s_waitcnt lgkmcnt(3)
	v_mfma_f32_16x16x32_bf16 v[92:95], v[128:131], v[160:163], 0
	v_mfma_f32_16x16x32_bf16 v[88:91], v[136:139], v[160:163], 0
	s_waitcnt lgkmcnt(1)
	v_mfma_f32_16x16x32_bf16 v[76:79], v[128:131], v[168:171], 0
	v_mfma_f32_16x16x32_bf16 v[72:75], v[136:139], v[168:171], 0
	v_mfma_f32_16x16x32_bf16 v[120:123], v[132:135], v[148:151], v[120:123]
	v_mfma_f32_16x16x32_bf16 v[124:127], v[140:143], v[148:151], v[124:127]
	v_mfma_f32_16x16x32_bf16 v[108:111], v[132:135], v[156:159], v[108:111]
	v_mfma_f32_16x16x32_bf16 v[104:107], v[140:143], v[156:159], v[104:107]
	v_mfma_f32_16x16x32_bf16 v[92:95], v[132:135], v[164:167], v[92:95]
	v_mfma_f32_16x16x32_bf16 v[88:91], v[140:143], v[164:167], v[88:91]
	s_waitcnt lgkmcnt(0)
	v_mfma_f32_16x16x32_bf16 v[76:79], v[132:135], v[172:175], v[76:79]
	v_mfma_f32_16x16x32_bf16 v[72:75], v[140:143], v[172:175], v[72:75]
	s_setprio 0
	s_barrier
	s_and_b32 s25, s18, 0xffff
	s_mov_b32 s26, s10
	s_mov_b32 s27, s11
	s_mov_b32 m0, s50
	ds_read_b128 v[176:179], v229
	ds_read_b128 v[180:183], v229 offset:1024
	ds_read_b128 v[192:195], v229 offset:2048
	ds_read_b128 v[196:199], v229 offset:3072
	buffer_load_dwordx4 v223, s[24:27], 0 offen lds
	s_mov_b32 m0, s51
	s_nop 0
	buffer_load_dwordx4 v225, s[24:27], 0 offen lds
	s_barrier
	s_waitcnt lgkmcnt(0)
	s_setprio 1
	s_waitcnt lgkmcnt(3)
	v_mfma_f32_16x16x32_bf16 v[116:119], v[176:179], v[144:147], 0
	s_waitcnt lgkmcnt(1)
	v_mfma_f32_16x16x32_bf16 v[112:115], v[192:195], v[144:147], 0
	v_mfma_f32_16x16x32_bf16 v[100:103], v[176:179], v[152:155], 0
	v_mfma_f32_16x16x32_bf16 v[96:99], v[192:195], v[152:155], 0
	v_mfma_f32_16x16x32_bf16 v[84:87], v[176:179], v[160:163], 0
	v_mfma_f32_16x16x32_bf16 v[80:83], v[192:195], v[160:163], 0
	v_mfma_f32_16x16x32_bf16 v[68:71], v[176:179], v[168:171], 0
	v_mfma_f32_16x16x32_bf16 v[64:67], v[192:195], v[168:171], 0
	v_mfma_f32_16x16x32_bf16 v[116:119], v[180:183], v[148:151], v[116:119]
	s_waitcnt lgkmcnt(0)
	v_mfma_f32_16x16x32_bf16 v[112:115], v[196:199], v[148:151], v[112:115]
	v_mfma_f32_16x16x32_bf16 v[100:103], v[180:183], v[156:159], v[100:103]
	v_mfma_f32_16x16x32_bf16 v[96:99], v[196:199], v[156:159], v[96:99]
	v_mfma_f32_16x16x32_bf16 v[84:87], v[180:183], v[164:167], v[84:87]
	v_mfma_f32_16x16x32_bf16 v[80:83], v[196:199], v[164:167], v[80:83]
	v_mfma_f32_16x16x32_bf16 v[68:71], v[180:183], v[172:175], v[68:71]
	v_mfma_f32_16x16x32_bf16 v[64:67], v[196:199], v[172:175], v[64:67]
	s_setprio 0
	s_and_b32 s29, s19, 0xffff
	s_mov_b32 s30, s10
	s_mov_b32 s31, s11
	s_mov_b32 m0, s49
	s_barrier
; #define PG8_STAGE(bufoff, gbase, voff) do { const __amdgpu_buffer_rsrc_t _r = __builtin_amdgcn_make_buffer_rsrc((void*)(gbase), (short)0, 0x7fffffff, 0x00020000); _Pragma("unroll") for (int _i = 0; _i < 2; ++_i) \
;         __builtin_amdgcn_raw_ptr_buffer_load_lds(_r, (LAS unsigned*)(lds + (bufoff) + ldsw + _i * 8192), 16, (int)(voff)[_i], 0, 0, 0); } while (0)
; #define PG8_LDA(dst, b, h) do { _Pragma("unroll") for (int m = 0; m < 4; ++m) _Pragma("unroll") for (int k = 0; k < 2; ++k) dst[m][k] = *(const LAS bf16x8*)(lds + PG8_SA(b, h) + aoff + m * 2048 + k * 1024); } while (0)
; #define PG8_MMA(ai, bj, At, Bt) do { __builtin_amdgcn_s_setprio(1); _Pragma("unroll") for (int k = 0; k < 2; ++k) _Pragma("unroll") for (int m = 0; m < 4; ++m) _Pragma("unroll") for (int n = 0; n < ((bj) == 1 ? NB1 : 2); ++n) \
;         acc[ai][bj][m][n] = __builtin_amdgcn_mfma_f32_16x16x32_bf16(Bt[n][k], At[m][k], acc[ai][bj][m][n], 0, 0, 0); __builtin_amdgcn_s_setprio(0); } while (0)
; #define PG8_WAIT_V(n) asm volatile("s_waitcnt vmcnt(" #n ")" ::: "memory")
; #define PG8_WAIT_L(n) asm volatile("s_waitcnt lgkmcnt(" #n ")" ::: "memory")
; #define PG8_BAR __builtin_amdgcn_s_barrier()
; #define PG8_SCHED __builtin_amdgcn_sched_barrier(0)
;     ...
;             PG8_LDA(At, 0, 1); PG8_STAGE(PG8_SA(0, 0), a2, voffA);
;             PG8_BAR; PG8_WAIT_L(0); PG8_MMA(1, 0, At, B0); PG8_BAR; PG8_SCHED;
;             PG8_STAGE(PG8_SB(0, 1), b2 + hstepB, voffB);
;             PG8_WAIT_V(6); PG8_BAR; PG8_MMA(1, 1, At, B1); PG8_BAR;
	ds_read_b128 v[144:147], v228 offset:16384
	ds_read_b128 v[148:151], v228 offset:17408
	ds_read_b128 v[152:155], v228 offset:18432
	ds_read_b128 v[156:159], v228 offset:19456
	ds_read_b128 v[160:163], v228 offset:20480
	ds_read_b128 v[164:167], v228 offset:21504
	ds_read_b128 v[168:171], v228 offset:22528
	ds_read_b128 v[172:175], v228 offset:23552
	buffer_load_dwordx4 v222, s[28:31], 0 offen lds
	s_mov_b32 m0, s52
	s_nop 0
	buffer_load_dwordx4 v224, s[28:31], 0 offen lds
	s_barrier
	s_waitcnt lgkmcnt(0)
	s_setprio 1
	s_waitcnt lgkmcnt(7)
	v_mfma_f32_16x16x32_bf16 v[60:63], v[128:131], v[144:147], 0
	v_mfma_f32_16x16x32_bf16 v[56:59], v[136:139], v[144:147], 0
	s_waitcnt lgkmcnt(5)
	v_mfma_f32_16x16x32_bf16 v[44:47], v[128:131], v[152:155], 0
	v_mfma_f32_16x16x32_bf16 v[40:43], v[136:139], v[152:155], 0
	s_waitcnt lgkmcnt(3)
	v_mfma_f32_16x16x32_bf16 v[28:31], v[128:131], v[160:163], 0
	v_mfma_f32_16x16x32_bf16 v[24:27], v[136:139], v[160:163], 0
	s_waitcnt lgkmcnt(1)
	v_mfma_f32_16x16x32_bf16 v[12:15], v[128:131], v[168:171], 0
	v_mfma_f32_16x16x32_bf16 v[8:11], v[136:139], v[168:171], 0
	v_mfma_f32_16x16x32_bf16 v[60:63], v[132:135], v[148:151], v[60:63]
	v_mfma_f32_16x16x32_bf16 v[56:59], v[140:143], v[148:151], v[56:59]
	v_mfma_f32_16x16x32_bf16 v[44:47], v[132:135], v[156:159], v[44:47]
	v_mfma_f32_16x16x32_bf16 v[40:43], v[140:143], v[156:159], v[40:43]
	v_mfma_f32_16x16x32_bf16 v[28:31], v[132:135], v[164:167], v[28:31]
	v_mfma_f32_16x16x32_bf16 v[24:27], v[140:143], v[164:167], v[24:27]
	s_waitcnt lgkmcnt(0)
	v_mfma_f32_16x16x32_bf16 v[12:15], v[132:135], v[172:175], v[12:15]
	v_mfma_f32_16x16x32_bf16 v[8:11], v[140:143], v[172:175], v[8:11]
	s_setprio 0
	s_barrier
	s_add_u32 s8, s24, s38
	s_addc_u32 s23, s18, s39
	s_and_b32 s9, s23, 0xffff
	s_mov_b32 m0, s53
	s_nop 0
	buffer_load_dwordx4 v223, s[8:11], 0 offen lds
	s_mov_b32 m0, s54
	s_nop 0
	buffer_load_dwordx4 v225, s[8:11], 0 offen lds
	s_waitcnt vmcnt(6)
	s_barrier
	s_setprio 1
	v_mfma_f32_16x16x32_bf16 v[52:55], v[176:179], v[144:147], 0
	v_mfma_f32_16x16x32_bf16 v[48:51], v[192:195], v[144:147], 0
	v_mfma_f32_16x16x32_bf16 v[36:39], v[176:179], v[152:155], 0
	v_mfma_f32_16x16x32_bf16 v[32:35], v[192:195], v[152:155], 0
	v_mfma_f32_16x16x32_bf16 v[20:23], v[176:179], v[160:163], 0
	v_mfma_f32_16x16x32_bf16 v[16:19], v[192:195], v[160:163], 0
	v_mfma_f32_16x16x32_bf16 v[4:7], v[176:179], v[168:171], 0
	v_mfma_f32_16x16x32_bf16 v[0:3], v[192:195], v[168:171], 0
	v_mfma_f32_16x16x32_bf16 v[52:55], v[180:183], v[148:151], v[52:55]
	v_mfma_f32_16x16x32_bf16 v[48:51], v[196:199], v[148:151], v[48:51]
	v_mfma_f32_16x16x32_bf16 v[36:39], v[180:183], v[156:159], v[36:39]
	v_mfma_f32_16x16x32_bf16 v[32:35], v[196:199], v[156:159], v[32:35]
	v_mfma_f32_16x16x32_bf16 v[20:23], v[180:183], v[164:167], v[20:23]
	v_mfma_f32_16x16x32_bf16 v[16:19], v[196:199], v[164:167], v[16:19]
	v_mfma_f32_16x16x32_bf16 v[4:7], v[180:183], v[172:175], v[4:7]
	v_mfma_f32_16x16x32_bf16 v[0:3], v[196:199], v[172:175], v[0:3]
	s_setprio 0
	s_barrier
	s_branch .Lkmid_1066
	.p2align 6
	s_nop 0
	s_nop 0
	s_nop 0
	s_nop 0
	s_nop 0
	s_nop 0
	s_nop 0
	s_nop 0
	s_nop 0
	s_nop 0
